# x-projection conv epilogue rewritten by hand: selects + fma + DPP fmacs (f32), 2.7x fewer VALU ops
# speedup vs baseline: 1.0255x; 1.0154x over previous
; #define PG8_STAGE(bufoff, gbase, voff) do { _Pragma("unroll") for (int _i = 0; _i < 2; ++_i) \
;         __builtin_amdgcn_global_load_lds((const __attribute__((address_space(1))) unsigned*)((const char*)(gbase) + (voff)[_i]), (LAS unsigned*)(lds + (bufoff) + ldsw + _i * 8192), 16, 0, 0); } while (0)
; #define PG8_LDA(dst, b, h) do { _Pragma("unroll") for (int m = 0; m < 4; ++m) _Pragma("unroll") for (int k = 0; k < 2; ++k) dst[m][k] = *(const LAS bf16x8*)(lds + PG8_SA(b, h) + aoff + m * 2048 + k * 1024); } while (0)
; #define PG8_LDB(dst, b, h) do { _Pragma("unroll") for (int n = 0; n < 2; ++n) _Pragma("unroll") for (int k = 0; k < 2; ++k) dst[n][k] = *(const LAS bf16x8*)(lds + PG8_SB(b, h) + boff + n * 2048 + k * 1024); } while (0)
; #define PG8_MMA(ai, bj, At, Bt) do { __builtin_amdgcn_s_setprio(1); _Pragma("unroll") for (int m = 0; m < 4; ++m) _Pragma("unroll") for (int n = 0; n < 2; ++n) _Pragma("unroll") for (int k = 0; k < 2; ++k) \
;         acc[ai][bj][m][n] = __builtin_amdgcn_mfma_f32_16x16x32_bf16(Bt[n][k], At[m][k], acc[ai][bj][m][n], 0, 0, 0); __builtin_amdgcn_s_setprio(0); } while (0)
; #define PG8_WAIT_L(n) asm volatile("s_waitcnt lgkmcnt(" #n ")" ::: "memory")
; #define PG8_BAR __builtin_amdgcn_s_barrier()
; #define PG8_SCHED __builtin_amdgcn_sched_barrier(0)
; template <class Epi>
; __device__ __forceinline__ void gemm_phase(LAS unsigned char* lds, const Gemm g, const StaticOrder& S_in, const Epi& E, int sw) {
;     ...
;             PG8_LDB(B0, 0, 0); PG8_SCHED; PG8_LDA(At, 0, 0); PG8_STAGE(PG8_SA(1, 1), a1 + hstepA, voffA);
;             PG8_WAIT_L(8); PG8_BAR; PG8_WAIT_L(0); PG8_MMA(0, 0, At, B0); PG8_BAR; PG8_SCHED;
;             PG8_LDB(B1, 0, 1); PG8_STAGE(PG8_SB(0, 0), b2, voffB);
;             PG8_BAR; PG8_WAIT_L(0); PG8_MMA(0, 1, At, B1); PG8_BAR;
;             PG8_LDA(At, 0, 1); PG8_STAGE(PG8_SA(0, 0), a2, voffA);
;             PG8_BAR; PG8_WAIT_L(0); PG8_MMA(1, 0, At, B0); PG8_BAR; PG8_SCHED;
.LBB0_261:
	s_add_u32 s8, s4, 0xfffc0080
	s_addc_u32 s9, s5, -1
	s_add_i32 s45, 0, 0x10000
	v_add_u32_e32 v118, s45, v171
	ds_read_b128 v[98:101], v118
	ds_read_b128 v[102:105], v118 offset:1024
	ds_read_b128 v[110:113], v118 offset:2048
	ds_read_b128 v[118:121], v118 offset:3072
	s_cmp_eq_u32 s44, 12
	s_cselect_b32 s11, s13, s9
	s_cselect_b32 s10, s27, s8
	s_cselect_b32 s9, s1, s7
	s_cselect_b32 s8, s0, s6
	v_lshl_add_u64 v[190:191], s[4:5], 0, v[178:179]
	s_add_i32 m0, s17, 0xc000
	ds_read_b128 v[126:129], v222
	ds_read_b128 v[130:133], v222 offset:1024
	ds_read_b128 v[134:137], v222 offset:2048
	ds_read_b128 v[138:141], v222 offset:3072
	ds_read_b128 v[162:165], v222 offset:4096
	ds_read_b128 v[166:169], v222 offset:5120
	ds_read_b128 v[182:185], v222 offset:6144
	ds_read_b128 v[186:189], v222 offset:7168
	global_load_lds_dwordx4 v[190:191], off
	v_lshl_add_u64 v[190:191], s[4:5], 0, v[180:181]
	s_add_i32 m0, s17, 0xe000
	s_nop 0
	global_load_lds_dwordx4 v[190:191], off
	s_waitcnt lgkmcnt(8)
	s_barrier
	s_waitcnt lgkmcnt(0)
	s_setprio 1
	s_waitcnt lgkmcnt(0)
	v_mfma_f32_16x16x32_bf16 v[158:161], v[98:101], v[126:129], v[158:161]
	v_mfma_f32_16x16x32_bf16 v[154:157], v[110:113], v[126:129], v[154:157]
	v_mfma_f32_16x16x32_bf16 v[150:153], v[98:101], v[134:137], v[150:153]
	v_mfma_f32_16x16x32_bf16 v[146:149], v[110:113], v[134:137], v[146:149]
	v_mfma_f32_16x16x32_bf16 v[142:145], v[98:101], v[162:165], v[142:145]
	v_mfma_f32_16x16x32_bf16 v[122:125], v[110:113], v[162:165], v[122:125]
	v_mfma_f32_16x16x32_bf16 v[114:117], v[98:101], v[182:185], v[114:117]
	v_mfma_f32_16x16x32_bf16 v[106:109], v[110:113], v[182:185], v[106:109]
	v_mfma_f32_16x16x32_bf16 v[158:161], v[102:105], v[130:133], v[158:161]
	v_mfma_f32_16x16x32_bf16 v[154:157], v[118:121], v[130:133], v[154:157]
	v_mfma_f32_16x16x32_bf16 v[150:153], v[102:105], v[138:141], v[150:153]
	v_mfma_f32_16x16x32_bf16 v[146:149], v[118:121], v[138:141], v[146:149]
	v_mfma_f32_16x16x32_bf16 v[142:145], v[102:105], v[166:169], v[142:145]
	v_mfma_f32_16x16x32_bf16 v[122:125], v[118:121], v[166:169], v[122:125]
	v_mfma_f32_16x16x32_bf16 v[114:117], v[102:105], v[186:189], v[114:117]
	v_mfma_f32_16x16x32_bf16 v[106:109], v[118:121], v[186:189], v[106:109]
	s_setprio 0
	s_barrier
	s_add_i32 s48, 0, 0x14000
	s_add_i32 s45, s45, s31
	v_add_u32_e32 v202, s48, v171
	v_lshl_add_u64 v[206:207], s[8:9], 0, v[0:1]
	s_mov_b32 m0, s45
	ds_read_b128 v[190:193], v202
	ds_read_b128 v[194:197], v202 offset:1024
	ds_read_b128 v[198:201], v202 offset:2048
	ds_read_b128 v[202:205], v202 offset:3072
	global_load_lds_dwordx4 v[206:207], off
	v_lshl_add_u64 v[208:209], s[8:9], 0, v[172:173]
	s_add_i32 m0, s45, 0x2000
	s_nop 0
	global_load_lds_dwordx4 v[208:209], off
	s_barrier
	s_waitcnt lgkmcnt(0)
	s_setprio 1
	s_waitcnt lgkmcnt(0)
	v_mfma_f32_16x16x32_bf16 v[62:65], v[190:193], v[126:129], v[62:65]
	v_mfma_f32_16x16x32_bf16 v[58:61], v[198:201], v[126:129], v[58:61]
	v_mfma_f32_16x16x32_bf16 v[54:57], v[190:193], v[134:137], v[54:57]
	v_mfma_f32_16x16x32_bf16 v[50:53], v[198:201], v[134:137], v[50:53]
	v_mfma_f32_16x16x32_bf16 v[46:49], v[190:193], v[162:165], v[46:49]
	v_mfma_f32_16x16x32_bf16 v[42:45], v[198:201], v[162:165], v[42:45]
	v_mfma_f32_16x16x32_bf16 v[38:41], v[190:193], v[182:185], v[38:41]
	v_mfma_f32_16x16x32_bf16 v[34:37], v[198:201], v[182:185], v[34:37]
	v_mfma_f32_16x16x32_bf16 v[62:65], v[194:197], v[130:133], v[62:65]
	v_mfma_f32_16x16x32_bf16 v[58:61], v[202:205], v[130:133], v[58:61]
	v_mfma_f32_16x16x32_bf16 v[54:57], v[194:197], v[138:141], v[54:57]
	v_mfma_f32_16x16x32_bf16 v[50:53], v[202:205], v[138:141], v[50:53]
	v_mfma_f32_16x16x32_bf16 v[46:49], v[194:197], v[166:169], v[46:49]
	v_mfma_f32_16x16x32_bf16 v[42:45], v[202:205], v[166:169], v[42:45]
	v_mfma_f32_16x16x32_bf16 v[38:41], v[194:197], v[186:189], v[38:41]
	v_mfma_f32_16x16x32_bf16 v[34:37], v[202:205], v[186:189], v[34:37]
	s_setprio 0
	s_mov_b32 m0, s17
	v_lshl_add_u64 v[210:211], s[10:11], 0, v[176:177]
	s_barrier
	ds_read_b128 v[126:129], v222 offset:16384
	ds_read_b128 v[130:133], v222 offset:17408
	ds_read_b128 v[134:137], v222 offset:18432
	ds_read_b128 v[138:141], v222 offset:19456
	ds_read_b128 v[162:165], v222 offset:20480
	ds_read_b128 v[166:169], v222 offset:21504
	ds_read_b128 v[182:185], v222 offset:22528
	ds_read_b128 v[186:189], v222 offset:23552
	global_load_lds_dwordx4 v[210:211], off
	v_lshl_add_u64 v[212:213], s[10:11], 0, v[174:175]
	s_mov_b32 m0, s36
	s_nop 0
	global_load_lds_dwordx4 v[212:213], off
	s_barrier
	s_waitcnt lgkmcnt(0)
	s_setprio 1
	s_waitcnt lgkmcnt(0)
	v_mfma_f32_16x16x32_bf16 v[94:97], v[98:101], v[126:129], v[94:97]
	v_mfma_f32_16x16x32_bf16 v[90:93], v[110:113], v[126:129], v[90:93]
	v_mfma_f32_16x16x32_bf16 v[86:89], v[98:101], v[134:137], v[86:89]
	v_mfma_f32_16x16x32_bf16 v[82:85], v[110:113], v[134:137], v[82:85]
	v_mfma_f32_16x16x32_bf16 v[78:81], v[98:101], v[162:165], v[78:81]
	v_mfma_f32_16x16x32_bf16 v[74:77], v[110:113], v[162:165], v[74:77]
	v_mfma_f32_16x16x32_bf16 v[70:73], v[98:101], v[182:185], v[70:73]
	v_mfma_f32_16x16x32_bf16 v[66:69], v[110:113], v[182:185], v[66:69]
	v_mfma_f32_16x16x32_bf16 v[94:97], v[102:105], v[130:133], v[94:97]
	v_mfma_f32_16x16x32_bf16 v[90:93], v[118:121], v[130:133], v[90:93]
	v_mfma_f32_16x16x32_bf16 v[86:89], v[102:105], v[138:141], v[86:89]
	v_mfma_f32_16x16x32_bf16 v[82:85], v[118:121], v[138:141], v[82:85]
	v_mfma_f32_16x16x32_bf16 v[78:81], v[102:105], v[166:169], v[78:81]
	v_mfma_f32_16x16x32_bf16 v[74:77], v[118:121], v[166:169], v[74:77]
	v_mfma_f32_16x16x32_bf16 v[70:73], v[102:105], v[186:189], v[70:73]
	v_mfma_f32_16x16x32_bf16 v[66:69], v[118:121], v[186:189], v[66:69]
	s_setprio 0
	s_barrier
; #define PG8_STAGE(bufoff, gbase, voff) do { _Pragma("unroll") for (int _i = 0; _i < 2; ++_i) \
;         __builtin_amdgcn_global_load_lds((const __attribute__((address_space(1))) unsigned*)((const char*)(gbase) + (voff)[_i]), (LAS unsigned*)(lds + (bufoff) + ldsw + _i * 8192), 16, 0, 0); } while (0)
; #define PG8_LDA(dst, b, h) do { _Pragma("unroll") for (int m = 0; m < 4; ++m) _Pragma("unroll") for (int k = 0; k < 2; ++k) dst[m][k] = *(const LAS bf16x8*)(lds + PG8_SA(b, h) + aoff + m * 2048 + k * 1024); } while (0)
; #define PG8_LDB(dst, b, h) do { _Pragma("unroll") for (int n = 0; n < 2; ++n) _Pragma("unroll") for (int k = 0; k < 2; ++k) dst[n][k] = *(const LAS bf16x8*)(lds + PG8_SB(b, h) + boff + n * 2048 + k * 1024); } while (0)
; #define PG8_MMA(ai, bj, At, Bt) do { __builtin_amdgcn_s_setprio(1); _Pragma("unroll") for (int m = 0; m < 4; ++m) _Pragma("unroll") for (int n = 0; n < 2; ++n) _Pragma("unroll") for (int k = 0; k < 2; ++k) \
;         acc[ai][bj][m][n] = __builtin_amdgcn_mfma_f32_16x16x32_bf16(Bt[n][k], At[m][k], acc[ai][bj][m][n], 0, 0, 0); __builtin_amdgcn_s_setprio(0); } while (0)
; #define PG8_WAIT_V(n) asm volatile("s_waitcnt vmcnt(" #n ")" ::: "memory")
; #define PG8_WAIT_L(n) asm volatile("s_waitcnt lgkmcnt(" #n ")" ::: "memory")
; #define PG8_BAR __builtin_amdgcn_s_barrier()
; #define PG8_SCHED __builtin_amdgcn_sched_barrier(0)
; template <class Epi>
; __device__ __forceinline__ void gemm_phase(LAS unsigned char* lds, const Gemm g, const StaticOrder& S_in, const Epi& E, int sw) {
;     ...
;             PG8_STAGE(PG8_SB(0, 1), b2 + hstepB, voffB);
;             PG8_WAIT_V(6); PG8_BAR; PG8_MMA(1, 1, At, B1); PG8_BAR;
;             PG8_LDB(B0, 1, 0); PG8_SCHED; PG8_LDA(At, 1, 0); PG8_STAGE(PG8_SA(0, 1), a2 + hstepA, voffA);
;             PG8_WAIT_L(8); PG8_BAR; PG8_WAIT_L(0); PG8_MMA(0, 0, At, B0); PG8_BAR; PG8_SCHED;
;             PG8_LDB(B1, 1, 1); PG8_STAGE(PG8_SB(1, 0), b3, voffB);
;             PG8_BAR; PG8_WAIT_L(0); PG8_MMA(0, 1, At, B1); PG8_BAR;
;             PG8_LDA(At, 1, 1); PG8_STAGE(PG8_SA(1, 0), a3, voffA);
;             PG8_BAR; PG8_WAIT_L(0); PG8_MMA(1, 0, At, B0); PG8_BAR; PG8_SCHED;
;             PG8_STAGE(PG8_SB(1, 1), b3 + hstepB, voffB);
	s_add_u32 s46, s8, 0x40000
	s_addc_u32 s47, s9, 0
	s_add_i32 s45, s48, s31
	v_lshl_add_u64 v[98:99], s[46:47], 0, v[0:1]
	s_mov_b32 m0, s45
	s_nop 0
	global_load_lds_dwordx4 v[98:99], off
	v_lshl_add_u64 v[98:99], s[46:47], 0, v[172:173]
	s_add_i32 m0, s45, 0x2000
	s_nop 0
	global_load_lds_dwordx4 v[98:99], off
	s_waitcnt vmcnt(6)
	s_barrier
	s_setprio 1
	v_mfma_f32_16x16x32_bf16 v[30:33], v[190:193], v[126:129], v[30:33]
	v_mfma_f32_16x16x32_bf16 v[26:29], v[198:201], v[126:129], v[26:29]
	v_mfma_f32_16x16x32_bf16 v[22:25], v[190:193], v[134:137], v[22:25]
	v_mfma_f32_16x16x32_bf16 v[18:21], v[198:201], v[134:137], v[18:21]
	v_mfma_f32_16x16x32_bf16 v[14:17], v[190:193], v[162:165], v[14:17]
	v_mfma_f32_16x16x32_bf16 v[10:13], v[198:201], v[162:165], v[10:13]
	v_mfma_f32_16x16x32_bf16 v[6:9], v[190:193], v[182:185], v[6:9]
	v_mfma_f32_16x16x32_bf16 v[2:5], v[198:201], v[182:185], v[2:5]
	v_mfma_f32_16x16x32_bf16 v[30:33], v[194:197], v[130:133], v[30:33]
	v_mfma_f32_16x16x32_bf16 v[26:29], v[202:205], v[130:133], v[26:29]
	v_mfma_f32_16x16x32_bf16 v[22:25], v[194:197], v[138:141], v[22:25]
	v_mfma_f32_16x16x32_bf16 v[18:21], v[202:205], v[138:141], v[18:21]
	v_mfma_f32_16x16x32_bf16 v[14:17], v[194:197], v[166:169], v[14:17]
	v_mfma_f32_16x16x32_bf16 v[10:13], v[202:205], v[166:169], v[10:13]
	v_mfma_f32_16x16x32_bf16 v[6:9], v[194:197], v[186:189], v[6:9]
	v_mfma_f32_16x16x32_bf16 v[2:5], v[202:205], v[186:189], v[2:5]
	s_setprio 0
	s_add_i32 s45, 0, 0x18000
	v_add_u32_e32 v118, s45, v171
	s_barrier
	ds_read_b128 v[98:101], v118
	ds_read_b128 v[102:105], v118 offset:1024
	ds_read_b128 v[110:113], v118 offset:2048
	ds_read_b128 v[118:121], v118 offset:3072
	s_add_u32 s10, s10, 0x40000
	s_addc_u32 s11, s11, 0
	s_mov_b32 m0, s37
	v_lshl_add_u64 v[190:191], s[10:11], 0, v[176:177]
	ds_read_b128 v[126:129], v222 offset:32768
	ds_read_b128 v[130:133], v222 offset:33792
	ds_read_b128 v[134:137], v222 offset:34816
	ds_read_b128 v[138:141], v222 offset:35840
	ds_read_b128 v[162:165], v222 offset:36864
	ds_read_b128 v[166:169], v222 offset:37888
	ds_read_b128 v[182:185], v222 offset:38912
	ds_read_b128 v[186:189], v222 offset:39936
	global_load_lds_dwordx4 v[190:191], off
	v_lshl_add_u64 v[190:191], s[10:11], 0, v[174:175]
	s_mov_b32 m0, s38
	s_nop 0
	global_load_lds_dwordx4 v[190:191], off
	s_waitcnt lgkmcnt(8)
	s_barrier
	s_waitcnt lgkmcnt(0)
	s_setprio 1
	s_waitcnt lgkmcnt(0)
	v_mfma_f32_16x16x32_bf16 v[158:161], v[98:101], v[126:129], v[158:161]
	v_mfma_f32_16x16x32_bf16 v[154:157], v[110:113], v[126:129], v[154:157]
	v_mfma_f32_16x16x32_bf16 v[150:153], v[98:101], v[134:137], v[150:153]
	v_mfma_f32_16x16x32_bf16 v[146:149], v[110:113], v[134:137], v[146:149]
	v_mfma_f32_16x16x32_bf16 v[142:145], v[98:101], v[162:165], v[142:145]
	v_mfma_f32_16x16x32_bf16 v[122:125], v[110:113], v[162:165], v[122:125]
	v_mfma_f32_16x16x32_bf16 v[114:117], v[98:101], v[182:185], v[114:117]
	v_mfma_f32_16x16x32_bf16 v[106:109], v[110:113], v[182:185], v[106:109]
	v_mfma_f32_16x16x32_bf16 v[158:161], v[102:105], v[130:133], v[158:161]
	v_mfma_f32_16x16x32_bf16 v[154:157], v[118:121], v[130:133], v[154:157]
	v_mfma_f32_16x16x32_bf16 v[150:153], v[102:105], v[138:141], v[150:153]
	v_mfma_f32_16x16x32_bf16 v[146:149], v[118:121], v[138:141], v[146:149]
	v_mfma_f32_16x16x32_bf16 v[142:145], v[102:105], v[166:169], v[142:145]
	v_mfma_f32_16x16x32_bf16 v[122:125], v[118:121], v[166:169], v[122:125]
	v_mfma_f32_16x16x32_bf16 v[114:117], v[102:105], v[186:189], v[114:117]
	v_mfma_f32_16x16x32_bf16 v[106:109], v[118:121], v[186:189], v[106:109]
	s_setprio 0
	s_barrier
	s_add_i32 s10, 0, 0x1c000
	s_add_i32 s11, s45, s31
	v_add_u32_e32 v202, s10, v171
	v_lshl_add_u64 v[206:207], v[206:207], 0, s[86:87]
	s_mov_b32 m0, s11
	ds_read_b128 v[190:193], v202
	ds_read_b128 v[194:197], v202 offset:1024
	ds_read_b128 v[198:201], v202 offset:2048
	ds_read_b128 v[202:205], v202 offset:3072
	global_load_lds_dwordx4 v[206:207], off
	v_lshl_add_u64 v[206:207], v[208:209], 0, s[86:87]
	s_add_i32 m0, s11, 0x2000
	s_nop 0
	global_load_lds_dwordx4 v[206:207], off
	s_barrier
	s_waitcnt lgkmcnt(0)
	s_setprio 1
	s_waitcnt lgkmcnt(0)
	v_mfma_f32_16x16x32_bf16 v[62:65], v[190:193], v[126:129], v[62:65]
	v_mfma_f32_16x16x32_bf16 v[58:61], v[198:201], v[126:129], v[58:61]
	v_mfma_f32_16x16x32_bf16 v[54:57], v[190:193], v[134:137], v[54:57]
	v_mfma_f32_16x16x32_bf16 v[50:53], v[198:201], v[134:137], v[50:53]
	v_mfma_f32_16x16x32_bf16 v[46:49], v[190:193], v[162:165], v[46:49]
	v_mfma_f32_16x16x32_bf16 v[42:45], v[198:201], v[162:165], v[42:45]
	v_mfma_f32_16x16x32_bf16 v[38:41], v[190:193], v[182:185], v[38:41]
	v_mfma_f32_16x16x32_bf16 v[34:37], v[198:201], v[182:185], v[34:37]
	v_mfma_f32_16x16x32_bf16 v[62:65], v[194:197], v[130:133], v[62:65]
	v_mfma_f32_16x16x32_bf16 v[58:61], v[202:205], v[130:133], v[58:61]
	v_mfma_f32_16x16x32_bf16 v[54:57], v[194:197], v[138:141], v[54:57]
	v_mfma_f32_16x16x32_bf16 v[50:53], v[202:205], v[138:141], v[50:53]
	v_mfma_f32_16x16x32_bf16 v[46:49], v[194:197], v[166:169], v[46:49]
	v_mfma_f32_16x16x32_bf16 v[42:45], v[202:205], v[166:169], v[42:45]
	v_mfma_f32_16x16x32_bf16 v[38:41], v[194:197], v[186:189], v[38:41]
	v_mfma_f32_16x16x32_bf16 v[34:37], v[202:205], v[186:189], v[34:37]
	s_setprio 0
	s_mov_b32 m0, s39
	v_lshl_add_u64 v[206:207], v[210:211], 0, s[86:87]
	s_barrier
	ds_read_b128 v[126:129], v222 offset:49152
	ds_read_b128 v[130:133], v222 offset:50176
	ds_read_b128 v[134:137], v222 offset:51200
	ds_read_b128 v[138:141], v222 offset:52224
	ds_read_b128 v[162:165], v222 offset:53248
	ds_read_b128 v[166:169], v222 offset:54272
	ds_read_b128 v[182:185], v222 offset:55296
	ds_read_b128 v[186:189], v222 offset:56320
	global_load_lds_dwordx4 v[206:207], off
	v_lshl_add_u64 v[206:207], v[212:213], 0, s[86:87]
	s_mov_b32 m0, s40
	s_nop 0
	global_load_lds_dwordx4 v[206:207], off
	s_barrier
; template <class Epi>
; __device__ __forceinline__ void gemm_phase(LAS unsigned char* lds, const Gemm g, const StaticOrder& S_in, const Epi& E, int sw) {
;     ...
;             PG8_WAIT_L(8); PG8_BAR; PG8_WAIT_L(0); PG8_MMA(0, 0, At, B0); PG8_BAR; PG8_SCHED;
;             PG8_LDB(B1, 1, 1); PG8_STAGE(PG8_SB(1, 0), b3, voffB);
;             PG8_BAR; PG8_WAIT_L(0); PG8_MMA(0, 1, At, B1); PG8_BAR;
;             PG8_LDA(At, 1, 1); PG8_STAGE(PG8_SA(1, 0), a3, voffA);
;             PG8_BAR; PG8_WAIT_L(0); PG8_MMA(1, 0, At, B0); PG8_BAR; PG8_SCHED;
;             PG8_STAGE(PG8_SB(1, 1), b3 + hstepB, voffB);
;             PG8_WAIT_V(6); PG8_BAR; PG8_MMA(1, 1, At, B1); PG8_BAR;
;     EPI_ZERO_INIT
;     __device__ __forceinline__ void operator()(AccRef acc, const Unit& u, int sw) const {
;         const int tid_ = ltid(sw), lane_ = tid_ & 63, wr = sw >> 2, wc = sw & 3, fr = lane_ & 15, fq = lane_ >> 4;
;         const int row0 = u.pm * BM + wr * 64 + fr, col0 = u.pn * BM + wc * 32 + 8 * fq;
;         const bool s1 = fr >= 15, s2 = fr >= 14, s3 = fr >= 13;
; #pragma unroll
;         for (int bj = 0; bj < 2; ++bj) { const int c = col0 + bj * HALF;
;             f32x4 w0[2], w1[2], w2[2], w3[2], bb[2];
; #pragma unroll
;             for (int n = 0; n < 2; ++n) { const int cc = bj * HALF + wc * 32 + 8 * fq + 4 * n;
;                 w0[n] = *(const LAS f32x4*)(cl + 0 * 256 + cc); w1[n] = *(const LAS f32x4*)(cl + 1 * 256 + cc); w2[n] = *(const LAS f32x4*)(cl + 2 * 256 + cc);
;                 w3[n] = *(const LAS f32x4*)(cl + 3 * 256 + cc); bb[n] = *(const LAS f32x4*)(cl + 4 * 256 + cc); }
; #pragma unroll
;             for (int ai = 0; ai < 2; ++ai)
; #pragma unroll
;                 for (int m = 0; m < 4; ++m) { const size_t off = (size_t)(row0 + ai * HALF + m * 16) * E + c;
;                     float y[8], x0[8];
; #pragma unroll
;                     for (int n = 0; n < 2; ++n)
; #pragma unroll
;                         for (int j = 0; j < 4; ++j) { const float cur = acc[ai][bj][m][n][j], prev = (m > 0) ? acc[ai][bj][m > 0 ? m - 1 : 0][n][j] : 0.f;
;                             const float x1 = row_ror<1>(s1 ? prev : cur), x2 = row_ror<2>(s2 ? prev : cur), x3 = row_ror<3>(s3 ? prev : cur);
;                             x0[4 * n + j] = cur;
;                             y[4 * n + j] = bb[n][j] + w0[n][j] * x3 + w1[n][j] * x2 + w2[n][j] * x1 + w3[n][j] * cur; }
	s_waitcnt lgkmcnt(0)
	s_setprio 1
	s_waitcnt lgkmcnt(0)
	v_mfma_f32_16x16x32_bf16 v[94:97], v[98:101], v[126:129], v[94:97]
	v_mfma_f32_16x16x32_bf16 v[90:93], v[110:113], v[126:129], v[90:93]
	v_mfma_f32_16x16x32_bf16 v[86:89], v[98:101], v[134:137], v[86:89]
	v_mfma_f32_16x16x32_bf16 v[82:85], v[110:113], v[134:137], v[82:85]
	v_mfma_f32_16x16x32_bf16 v[78:81], v[98:101], v[162:165], v[78:81]
	v_mfma_f32_16x16x32_bf16 v[74:77], v[110:113], v[162:165], v[74:77]
	v_mfma_f32_16x16x32_bf16 v[70:73], v[98:101], v[182:185], v[70:73]
	v_mfma_f32_16x16x32_bf16 v[66:69], v[110:113], v[182:185], v[66:69]
	v_mfma_f32_16x16x32_bf16 v[94:97], v[102:105], v[130:133], v[94:97]
	v_mfma_f32_16x16x32_bf16 v[90:93], v[118:121], v[130:133], v[90:93]
	v_mfma_f32_16x16x32_bf16 v[86:89], v[102:105], v[138:141], v[86:89]
	v_mfma_f32_16x16x32_bf16 v[82:85], v[118:121], v[138:141], v[82:85]
	v_mfma_f32_16x16x32_bf16 v[78:81], v[102:105], v[166:169], v[78:81]
	v_mfma_f32_16x16x32_bf16 v[74:77], v[118:121], v[166:169], v[74:77]
	v_mfma_f32_16x16x32_bf16 v[70:73], v[102:105], v[186:189], v[70:73]
	v_mfma_f32_16x16x32_bf16 v[66:69], v[118:121], v[186:189], v[66:69]
	s_setprio 0
	s_barrier
	s_add_u32 s8, s8, 0x40080
	s_addc_u32 s9, s9, 0
	s_add_i32 s10, s10, s31
	v_lshl_add_u64 v[98:99], s[8:9], 0, v[0:1]
	s_mov_b32 m0, s10
	s_nop 0
	global_load_lds_dwordx4 v[98:99], off
	v_lshl_add_u64 v[98:99], s[8:9], 0, v[172:173]
	s_add_i32 m0, s10, 0x2000
	s_nop 0
	global_load_lds_dwordx4 v[98:99], off
	s_waitcnt vmcnt(6)
	s_barrier
	s_setprio 1
	v_mfma_f32_16x16x32_bf16 v[30:33], v[190:193], v[126:129], v[30:33]
	v_mfma_f32_16x16x32_bf16 v[26:29], v[198:201], v[126:129], v[26:29]
	v_mfma_f32_16x16x32_bf16 v[22:25], v[190:193], v[134:137], v[22:25]
	v_mfma_f32_16x16x32_bf16 v[18:21], v[198:201], v[134:137], v[18:21]
	v_mfma_f32_16x16x32_bf16 v[14:17], v[190:193], v[162:165], v[14:17]
	v_mfma_f32_16x16x32_bf16 v[10:13], v[198:201], v[162:165], v[10:13]
	v_mfma_f32_16x16x32_bf16 v[6:9], v[190:193], v[182:185], v[6:9]
	v_mfma_f32_16x16x32_bf16 v[2:5], v[198:201], v[182:185], v[2:5]
	v_mfma_f32_16x16x32_bf16 v[30:33], v[194:197], v[130:133], v[30:33]
	v_mfma_f32_16x16x32_bf16 v[26:29], v[202:205], v[130:133], v[26:29]
	v_mfma_f32_16x16x32_bf16 v[22:25], v[194:197], v[138:141], v[22:25]
	v_mfma_f32_16x16x32_bf16 v[18:21], v[202:205], v[138:141], v[18:21]
	v_mfma_f32_16x16x32_bf16 v[14:17], v[194:197], v[166:169], v[14:17]
	v_mfma_f32_16x16x32_bf16 v[10:13], v[202:205], v[166:169], v[10:13]
	v_mfma_f32_16x16x32_bf16 v[6:9], v[194:197], v[186:189], v[6:9]
	v_mfma_f32_16x16x32_bf16 v[2:5], v[202:205], v[186:189], v[2:5]
	s_setprio 0
	s_add_i32 s44, s44, 2
	s_add_u32 s4, s4, 0x100
	s_addc_u32 s5, s5, 0
	s_add_u32 s6, s6, 0x100
	s_addc_u32 s7, s7, 0
	s_cmp_gt_u32 s44, 13
	s_barrier
	s_cbranch_scc0 .LBB0_261
	v_mbcnt_lo_u32_b32 v140, -1, 0
	v_mbcnt_hi_u32_b32 v140, -1, v140
	v_lshl_add_u32 v140, s75, 6, v140
	s_lshl_b32 s4, s12, 8
	s_add_i32 s4, s4, s3
	v_and_b32_e32 v223, 15, v140
	v_lshrrev_b32_e32 v141, 1, v140
	v_and_b32_e32 v141, 24, v141
	v_or_b32_e32 v140, s4, v223
	v_or_b32_e32 v224, s85, v141
	v_lshlrev_b32_e32 v226, 12, v140
	v_or_b32_e32 v141, s42, v141
	v_lshlrev_b32_e32 v224, 2, v224
	v_lshl_add_u32 v226, v141, 1, v226
	v_add_u32_e32 v224, 0x20400, v224
	v_cmp_le_u32_e64 s[4:5], 15, v223
	v_cmp_le_u32_e64 s[6:7], 14, v223
	v_cmp_le_u32_e64 s[8:9], 13, v223
	v_cmp_le_u32_e64 s[10:11], 3, v223
	v_add_u32_e32 v98, 0x10000, v226
	v_add_u32_e32 v99, 0x20000, v226
	v_add_u32_e32 v100, 0x30000, v226
	v_add_u32_e32 v101, 0x80000, v226
	v_add_u32_e32 v102, 0x90000, v226
	v_add_u32_e32 v103, 0xa0000, v226
	v_add_u32_e32 v104, 0xb0000, v226
	ds_read_b128 v[182:185], v224 offset:0
	ds_read_b128 v[186:189], v224 offset:16
	ds_read_b128 v[190:193], v224 offset:1024
	ds_read_b128 v[194:197], v224 offset:1040
	ds_read_b128 v[198:201], v224 offset:2048
	ds_read_b128 v[202:205], v224 offset:2064
	ds_read_b128 v[206:209], v224 offset:3072
	ds_read_b128 v[210:213], v224 offset:3088
	ds_read_b128 v[214:217], v224 offset:4096
	ds_read_b128 v[218:221], v224 offset:4112
	s_waitcnt lgkmcnt(0)
	v_cndmask_b32_e64 v126, v158, 0, s[4:5]
	v_cndmask_b32_e64 v127, v158, 0, s[6:7]
	v_cndmask_b32_e64 v128, v158, 0, s[8:9]
	v_fma_f32 v132, v206, v158, v214
	v_cndmask_b32_e64 v129, v159, 0, s[4:5]
	v_fmac_f32_dpp v132, v126, v198 row_ror:1 row_mask:0xf bank_mask:0xf
	v_cndmask_b32_e64 v130, v159, 0, s[6:7]
	v_fmac_f32_dpp v132, v127, v190 row_ror:2 row_mask:0xf bank_mask:0xf
	v_cndmask_b32_e64 v131, v159, 0, s[8:9]
	v_fmac_f32_dpp v132, v128, v182 row_ror:3 row_mask:0xf bank_mask:0xf
	v_fma_f32 v133, v207, v159, v215
	v_cndmask_b32_e64 v126, v160, 0, s[4:5]
	v_fmac_f32_dpp v133, v129, v199 row_ror:1 row_mask:0xf bank_mask:0xf
	v_cndmask_b32_e64 v127, v160, 0, s[6:7]
	v_fmac_f32_dpp v133, v130, v191 row_ror:2 row_mask:0xf bank_mask:0xf
	v_cndmask_b32_e64 v128, v160, 0, s[8:9]
	v_fmac_f32_dpp v133, v131, v183 row_ror:3 row_mask:0xf bank_mask:0xf
	v_fma_f32 v134, v208, v160, v216
	v_cndmask_b32_e64 v129, v161, 0, s[4:5]
	v_fmac_f32_dpp v134, v126, v200 row_ror:1 row_mask:0xf bank_mask:0xf
	v_cndmask_b32_e64 v130, v161, 0, s[6:7]
	v_fmac_f32_dpp v134, v127, v192 row_ror:2 row_mask:0xf bank_mask:0xf
	v_cndmask_b32_e64 v131, v161, 0, s[8:9]
	v_fmac_f32_dpp v134, v128, v184 row_ror:3 row_mask:0xf bank_mask:0xf
	v_fma_f32 v135, v209, v161, v217
	v_cndmask_b32_e64 v126, v154, 0, s[4:5]
	v_fmac_f32_dpp v135, v129, v201 row_ror:1 row_mask:0xf bank_mask:0xf
	v_cndmask_b32_e64 v127, v154, 0, s[6:7]
	v_fmac_f32_dpp v135, v130, v193 row_ror:2 row_mask:0xf bank_mask:0xf
	v_cndmask_b32_e64 v128, v154, 0, s[8:9]
; __device__ __forceinline__ unsigned cvt_pk_bf16(float lo, float hi) { unsigned r; asm volatile("v_cvt_pk_bf16_f32 %0, %1, %2" : "=v"(r) : "v"(lo), "v"(hi)); return r; }
; template <int K> __device__ __forceinline__ float row_ror(float v) { return __int_as_float(__builtin_amdgcn_update_dpp(0, __float_as_int(v), 0x120 + K, 0xF, 0xF, false)); }
;     EPI_ZERO_INIT
;     __device__ __forceinline__ void operator()(AccRef acc, const Unit& u, int sw) const {
;     ...
;                 for (int m = 0; m < 4; ++m) { const size_t off = (size_t)(row0 + ai * HALF + m * 16) * E + c;
;                     float y[8], x0[8];
; #pragma unroll
;                     for (int n = 0; n < 2; ++n)
; #pragma unroll
;                         for (int j = 0; j < 4; ++j) { const float cur = acc[ai][bj][m][n][j], prev = (m > 0) ? acc[ai][bj][m > 0 ? m - 1 : 0][n][j] : 0.f;
;                             const float x1 = row_ror<1>(s1 ? prev : cur), x2 = row_ror<2>(s2 ? prev : cur), x3 = row_ror<3>(s3 ? prev : cur);
;                             x0[4 * n + j] = cur;
;                             y[4 * n + j] = bb[n][j] + w0[n][j] * x3 + w1[n][j] * x2 + w2[n][j] * x1 + w3[n][j] * cur; }
;                     if (m > 0 || fr >= 3) { u32x4 w; w.x = cvt_pk_bf16(y[0], y[1]); w.y = cvt_pk_bf16(y[2], y[3]); w.z = cvt_pk_bf16(y[4], y[5]); w.w = cvt_pk_bf16(y[6], y[7]);
;                         *(u32x4*)(XC + off) = w; }
;                     if ((m == 0 && fr < 3) || (m == 3 && fr >= 13)) { u32x4 w; w.x = cvt_pk_bf16(x0[0], x0[1]); w.y = cvt_pk_bf16(x0[2], x0[3]); w.z = cvt_pk_bf16(x0[4], x0[5]); w.w = cvt_pk_bf16(x0[6], x0[7]);
;                         *(u32x4*)(XBE + off) = w; } }
	v_fmac_f32_dpp v135, v131, v185 row_ror:3 row_mask:0xf bank_mask:0xf
	v_fma_f32 v136, v210, v154, v218
	v_cndmask_b32_e64 v129, v155, 0, s[4:5]
	v_fmac_f32_dpp v136, v126, v202 row_ror:1 row_mask:0xf bank_mask:0xf
	v_cndmask_b32_e64 v130, v155, 0, s[6:7]
	v_fmac_f32_dpp v136, v127, v194 row_ror:2 row_mask:0xf bank_mask:0xf
	v_cndmask_b32_e64 v131, v155, 0, s[8:9]
	v_fmac_f32_dpp v136, v128, v186 row_ror:3 row_mask:0xf bank_mask:0xf
	v_fma_f32 v137, v211, v155, v219
	v_cndmask_b32_e64 v126, v156, 0, s[4:5]
	v_fmac_f32_dpp v137, v129, v203 row_ror:1 row_mask:0xf bank_mask:0xf
	v_cndmask_b32_e64 v127, v156, 0, s[6:7]
	v_fmac_f32_dpp v137, v130, v195 row_ror:2 row_mask:0xf bank_mask:0xf
	v_cndmask_b32_e64 v128, v156, 0, s[8:9]
	v_fmac_f32_dpp v137, v131, v187 row_ror:3 row_mask:0xf bank_mask:0xf
	v_fma_f32 v138, v212, v156, v220
	v_cndmask_b32_e64 v129, v157, 0, s[4:5]
	v_fmac_f32_dpp v138, v126, v204 row_ror:1 row_mask:0xf bank_mask:0xf
	v_cndmask_b32_e64 v130, v157, 0, s[6:7]
	v_fmac_f32_dpp v138, v127, v196 row_ror:2 row_mask:0xf bank_mask:0xf
	v_cndmask_b32_e64 v131, v157, 0, s[8:9]
	v_fmac_f32_dpp v138, v128, v188 row_ror:3 row_mask:0xf bank_mask:0xf
	v_fma_f32 v139, v213, v157, v221
	v_fmac_f32_dpp v139, v129, v205 row_ror:1 row_mask:0xf bank_mask:0xf
	v_fmac_f32_dpp v139, v130, v197 row_ror:2 row_mask:0xf bank_mask:0xf
	v_fmac_f32_dpp v139, v131, v189 row_ror:3 row_mask:0xf bank_mask:0xf
	v_cvt_pk_bf16_f32 v162, v132, v133
	v_cvt_pk_bf16_f32 v163, v134, v135
	v_cvt_pk_bf16_f32 v164, v136, v137
	v_cvt_pk_bf16_f32 v165, v138, v139
	v_cvt_pk_bf16_f32 v110, v158, v159
	v_cvt_pk_bf16_f32 v111, v160, v161
	v_cvt_pk_bf16_f32 v112, v154, v155
	v_cvt_pk_bf16_f32 v113, v156, v157
	s_mov_b64 exec, s[10:11]
	global_store_dwordx4 v226, v[162:165], s[20:21]
	s_not_b64 exec, exec
	global_store_dwordx4 v226, v[110:113], s[22:23]
	s_mov_b64 exec, -1
	s_nop 1
	v_cndmask_b32_e64 v126, v150, v158, s[4:5]
	v_cndmask_b32_e64 v127, v150, v158, s[6:7]
	v_cndmask_b32_e64 v128, v150, v158, s[8:9]
	v_fma_f32 v132, v206, v150, v214
	v_cndmask_b32_e64 v129, v151, v159, s[4:5]
	v_fmac_f32_dpp v132, v126, v198 row_ror:1 row_mask:0xf bank_mask:0xf
	v_cndmask_b32_e64 v130, v151, v159, s[6:7]
	v_fmac_f32_dpp v132, v127, v190 row_ror:2 row_mask:0xf bank_mask:0xf
	v_cndmask_b32_e64 v131, v151, v159, s[8:9]
	v_fmac_f32_dpp v132, v128, v182 row_ror:3 row_mask:0xf bank_mask:0xf
	v_fma_f32 v133, v207, v151, v215
	v_cndmask_b32_e64 v126, v152, v160, s[4:5]
	v_fmac_f32_dpp v133, v129, v199 row_ror:1 row_mask:0xf bank_mask:0xf
	v_cndmask_b32_e64 v127, v152, v160, s[6:7]
	v_fmac_f32_dpp v133, v130, v191 row_ror:2 row_mask:0xf bank_mask:0xf
	v_cndmask_b32_e64 v128, v152, v160, s[8:9]
	v_fmac_f32_dpp v133, v131, v183 row_ror:3 row_mask:0xf bank_mask:0xf
	v_fma_f32 v134, v208, v152, v216
	v_cndmask_b32_e64 v129, v153, v161, s[4:5]
	v_fmac_f32_dpp v134, v126, v200 row_ror:1 row_mask:0xf bank_mask:0xf
	v_cndmask_b32_e64 v130, v153, v161, s[6:7]
	v_fmac_f32_dpp v134, v127, v192 row_ror:2 row_mask:0xf bank_mask:0xf
	v_cndmask_b32_e64 v131, v153, v161, s[8:9]
	v_fmac_f32_dpp v134, v128, v184 row_ror:3 row_mask:0xf bank_mask:0xf
	v_fma_f32 v135, v209, v153, v217
	v_cndmask_b32_e64 v126, v146, v154, s[4:5]
	v_fmac_f32_dpp v135, v129, v201 row_ror:1 row_mask:0xf bank_mask:0xf
	v_cndmask_b32_e64 v127, v146, v154, s[6:7]
	v_fmac_f32_dpp v135, v130, v193 row_ror:2 row_mask:0xf bank_mask:0xf
	v_cndmask_b32_e64 v128, v146, v154, s[8:9]
	v_fmac_f32_dpp v135, v131, v185 row_ror:3 row_mask:0xf bank_mask:0xf
	v_fma_f32 v136, v210, v146, v218
	v_cndmask_b32_e64 v129, v147, v155, s[4:5]
	v_fmac_f32_dpp v136, v126, v202 row_ror:1 row_mask:0xf bank_mask:0xf
	v_cndmask_b32_e64 v130, v147, v155, s[6:7]
	v_fmac_f32_dpp v136, v127, v194 row_ror:2 row_mask:0xf bank_mask:0xf
	v_cndmask_b32_e64 v131, v147, v155, s[8:9]
	v_fmac_f32_dpp v136, v128, v186 row_ror:3 row_mask:0xf bank_mask:0xf
	v_fma_f32 v137, v211, v147, v219
	v_cndmask_b32_e64 v126, v148, v156, s[4:5]
	v_fmac_f32_dpp v137, v129, v203 row_ror:1 row_mask:0xf bank_mask:0xf
	v_cndmask_b32_e64 v127, v148, v156, s[6:7]
	v_fmac_f32_dpp v137, v130, v195 row_ror:2 row_mask:0xf bank_mask:0xf
	v_cndmask_b32_e64 v128, v148, v156, s[8:9]
	v_fmac_f32_dpp v137, v131, v187 row_ror:3 row_mask:0xf bank_mask:0xf
	v_fma_f32 v138, v212, v148, v220
	v_cndmask_b32_e64 v129, v149, v157, s[4:5]
	v_fmac_f32_dpp v138, v126, v204 row_ror:1 row_mask:0xf bank_mask:0xf
	v_cndmask_b32_e64 v130, v149, v157, s[6:7]
	v_fmac_f32_dpp v138, v127, v196 row_ror:2 row_mask:0xf bank_mask:0xf
	v_cndmask_b32_e64 v131, v149, v157, s[8:9]
	v_fmac_f32_dpp v138, v128, v188 row_ror:3 row_mask:0xf bank_mask:0xf
	v_fma_f32 v139, v213, v149, v221
	v_fmac_f32_dpp v139, v129, v205 row_ror:1 row_mask:0xf bank_mask:0xf
	v_fmac_f32_dpp v139, v130, v197 row_ror:2 row_mask:0xf bank_mask:0xf
	v_fmac_f32_dpp v139, v131, v189 row_ror:3 row_mask:0xf bank_mask:0xf
	v_cvt_pk_bf16_f32 v166, v132, v133
	v_cvt_pk_bf16_f32 v167, v134, v135
	v_cvt_pk_bf16_f32 v168, v136, v137
	v_cvt_pk_bf16_f32 v169, v138, v139
	global_store_dwordx4 v98, v[166:169], s[20:21]
	s_nop 1
	v_cndmask_b32_e64 v126, v142, v150, s[4:5]
	v_cndmask_b32_e64 v127, v142, v150, s[6:7]
	v_cndmask_b32_e64 v128, v142, v150, s[8:9]
	v_fma_f32 v132, v206, v142, v214
	v_cndmask_b32_e64 v129, v143, v151, s[4:5]
	v_fmac_f32_dpp v132, v126, v198 row_ror:1 row_mask:0xf bank_mask:0xf
	v_cndmask_b32_e64 v130, v143, v151, s[6:7]
	v_fmac_f32_dpp v132, v127, v190 row_ror:2 row_mask:0xf bank_mask:0xf
	v_cndmask_b32_e64 v131, v143, v151, s[8:9]
	v_fmac_f32_dpp v132, v128, v182 row_ror:3 row_mask:0xf bank_mask:0xf
	v_fma_f32 v133, v207, v143, v215
; __device__ __forceinline__ unsigned cvt_pk_bf16(float lo, float hi) { unsigned r; asm volatile("v_cvt_pk_bf16_f32 %0, %1, %2" : "=v"(r) : "v"(lo), "v"(hi)); return r; }
; template <int K> __device__ __forceinline__ float row_ror(float v) { return __int_as_float(__builtin_amdgcn_update_dpp(0, __float_as_int(v), 0x120 + K, 0xF, 0xF, false)); }
;     EPI_ZERO_INIT
;     __device__ __forceinline__ void operator()(AccRef acc, const Unit& u, int sw) const {
;     ...
;                 for (int m = 0; m < 4; ++m) { const size_t off = (size_t)(row0 + ai * HALF + m * 16) * E + c;
;                     float y[8], x0[8];
; #pragma unroll
;                     for (int n = 0; n < 2; ++n)
; #pragma unroll
;                         for (int j = 0; j < 4; ++j) { const float cur = acc[ai][bj][m][n][j], prev = (m > 0) ? acc[ai][bj][m > 0 ? m - 1 : 0][n][j] : 0.f;
;                             const float x1 = row_ror<1>(s1 ? prev : cur), x2 = row_ror<2>(s2 ? prev : cur), x3 = row_ror<3>(s3 ? prev : cur);
;                             x0[4 * n + j] = cur;
;                             y[4 * n + j] = bb[n][j] + w0[n][j] * x3 + w1[n][j] * x2 + w2[n][j] * x1 + w3[n][j] * cur; }
;                     if (m > 0 || fr >= 3) { u32x4 w; w.x = cvt_pk_bf16(y[0], y[1]); w.y = cvt_pk_bf16(y[2], y[3]); w.z = cvt_pk_bf16(y[4], y[5]); w.w = cvt_pk_bf16(y[6], y[7]);
;                         *(u32x4*)(XC + off) = w; }
;                     if ((m == 0 && fr < 3) || (m == 3 && fr >= 13)) { u32x4 w; w.x = cvt_pk_bf16(x0[0], x0[1]); w.y = cvt_pk_bf16(x0[2], x0[3]); w.z = cvt_pk_bf16(x0[4], x0[5]); w.w = cvt_pk_bf16(x0[6], x0[7]);
;                         *(u32x4*)(XBE + off) = w; } }
	v_cndmask_b32_e64 v126, v144, v152, s[4:5]
	v_fmac_f32_dpp v133, v129, v199 row_ror:1 row_mask:0xf bank_mask:0xf
	v_cndmask_b32_e64 v127, v144, v152, s[6:7]
	v_fmac_f32_dpp v133, v130, v191 row_ror:2 row_mask:0xf bank_mask:0xf
	v_cndmask_b32_e64 v128, v144, v152, s[8:9]
	v_fmac_f32_dpp v133, v131, v183 row_ror:3 row_mask:0xf bank_mask:0xf
	v_fma_f32 v134, v208, v144, v216
	v_cndmask_b32_e64 v129, v145, v153, s[4:5]
	v_fmac_f32_dpp v134, v126, v200 row_ror:1 row_mask:0xf bank_mask:0xf
	v_cndmask_b32_e64 v130, v145, v153, s[6:7]
	v_fmac_f32_dpp v134, v127, v192 row_ror:2 row_mask:0xf bank_mask:0xf
	v_cndmask_b32_e64 v131, v145, v153, s[8:9]
	v_fmac_f32_dpp v134, v128, v184 row_ror:3 row_mask:0xf bank_mask:0xf
	v_fma_f32 v135, v209, v145, v217
	v_cndmask_b32_e64 v126, v122, v146, s[4:5]
	v_fmac_f32_dpp v135, v129, v201 row_ror:1 row_mask:0xf bank_mask:0xf
	v_cndmask_b32_e64 v127, v122, v146, s[6:7]
	v_fmac_f32_dpp v135, v130, v193 row_ror:2 row_mask:0xf bank_mask:0xf
	v_cndmask_b32_e64 v128, v122, v146, s[8:9]
	v_fmac_f32_dpp v135, v131, v185 row_ror:3 row_mask:0xf bank_mask:0xf
	v_fma_f32 v136, v210, v122, v218
	v_cndmask_b32_e64 v129, v123, v147, s[4:5]
	v_fmac_f32_dpp v136, v126, v202 row_ror:1 row_mask:0xf bank_mask:0xf
	v_cndmask_b32_e64 v130, v123, v147, s[6:7]
	v_fmac_f32_dpp v136, v127, v194 row_ror:2 row_mask:0xf bank_mask:0xf
	v_cndmask_b32_e64 v131, v123, v147, s[8:9]
	v_fmac_f32_dpp v136, v128, v186 row_ror:3 row_mask:0xf bank_mask:0xf
	v_fma_f32 v137, v211, v123, v219
	v_cndmask_b32_e64 v126, v124, v148, s[4:5]
	v_fmac_f32_dpp v137, v129, v203 row_ror:1 row_mask:0xf bank_mask:0xf
	v_cndmask_b32_e64 v127, v124, v148, s[6:7]
	v_fmac_f32_dpp v137, v130, v195 row_ror:2 row_mask:0xf bank_mask:0xf
	v_cndmask_b32_e64 v128, v124, v148, s[8:9]
	v_fmac_f32_dpp v137, v131, v187 row_ror:3 row_mask:0xf bank_mask:0xf
	v_fma_f32 v138, v212, v124, v220
	v_cndmask_b32_e64 v129, v125, v149, s[4:5]
	v_fmac_f32_dpp v138, v126, v204 row_ror:1 row_mask:0xf bank_mask:0xf
	v_cndmask_b32_e64 v130, v125, v149, s[6:7]
	v_fmac_f32_dpp v138, v127, v196 row_ror:2 row_mask:0xf bank_mask:0xf
	v_cndmask_b32_e64 v131, v125, v149, s[8:9]
	v_fmac_f32_dpp v138, v128, v188 row_ror:3 row_mask:0xf bank_mask:0xf
	v_fma_f32 v139, v213, v125, v221
	v_fmac_f32_dpp v139, v129, v205 row_ror:1 row_mask:0xf bank_mask:0xf
	v_fmac_f32_dpp v139, v130, v197 row_ror:2 row_mask:0xf bank_mask:0xf
	v_fmac_f32_dpp v139, v131, v189 row_ror:3 row_mask:0xf bank_mask:0xf
	v_cvt_pk_bf16_f32 v162, v132, v133
	v_cvt_pk_bf16_f32 v163, v134, v135
	v_cvt_pk_bf16_f32 v164, v136, v137
	v_cvt_pk_bf16_f32 v165, v138, v139
	global_store_dwordx4 v99, v[162:165], s[20:21]
	s_nop 1
	v_cndmask_b32_e64 v126, v114, v142, s[4:5]
	v_cndmask_b32_e64 v127, v114, v142, s[6:7]
	v_cndmask_b32_e64 v128, v114, v142, s[8:9]
	v_fma_f32 v132, v206, v114, v214
	v_cndmask_b32_e64 v129, v115, v143, s[4:5]
	v_fmac_f32_dpp v132, v126, v198 row_ror:1 row_mask:0xf bank_mask:0xf
	v_cndmask_b32_e64 v130, v115, v143, s[6:7]
	v_fmac_f32_dpp v132, v127, v190 row_ror:2 row_mask:0xf bank_mask:0xf
	v_cndmask_b32_e64 v131, v115, v143, s[8:9]
	v_fmac_f32_dpp v132, v128, v182 row_ror:3 row_mask:0xf bank_mask:0xf
	v_fma_f32 v133, v207, v115, v215
	v_cndmask_b32_e64 v126, v116, v144, s[4:5]
	v_fmac_f32_dpp v133, v129, v199 row_ror:1 row_mask:0xf bank_mask:0xf
	v_cndmask_b32_e64 v127, v116, v144, s[6:7]
	v_fmac_f32_dpp v133, v130, v191 row_ror:2 row_mask:0xf bank_mask:0xf
	v_cndmask_b32_e64 v128, v116, v144, s[8:9]
	v_fmac_f32_dpp v133, v131, v183 row_ror:3 row_mask:0xf bank_mask:0xf
	v_fma_f32 v134, v208, v116, v216
	v_cndmask_b32_e64 v129, v117, v145, s[4:5]
	v_fmac_f32_dpp v134, v126, v200 row_ror:1 row_mask:0xf bank_mask:0xf
	v_cndmask_b32_e64 v130, v117, v145, s[6:7]
	v_fmac_f32_dpp v134, v127, v192 row_ror:2 row_mask:0xf bank_mask:0xf
	v_cndmask_b32_e64 v131, v117, v145, s[8:9]
	v_fmac_f32_dpp v134, v128, v184 row_ror:3 row_mask:0xf bank_mask:0xf
	v_fma_f32 v135, v209, v117, v217
	v_cndmask_b32_e64 v126, v106, v122, s[4:5]
	v_fmac_f32_dpp v135, v129, v201 row_ror:1 row_mask:0xf bank_mask:0xf
	v_cndmask_b32_e64 v127, v106, v122, s[6:7]
	v_fmac_f32_dpp v135, v130, v193 row_ror:2 row_mask:0xf bank_mask:0xf
	v_cndmask_b32_e64 v128, v106, v122, s[8:9]
	v_fmac_f32_dpp v135, v131, v185 row_ror:3 row_mask:0xf bank_mask:0xf
	v_fma_f32 v136, v210, v106, v218
	v_cndmask_b32_e64 v129, v107, v123, s[4:5]
	v_fmac_f32_dpp v136, v126, v202 row_ror:1 row_mask:0xf bank_mask:0xf
	v_cndmask_b32_e64 v130, v107, v123, s[6:7]
	v_fmac_f32_dpp v136, v127, v194 row_ror:2 row_mask:0xf bank_mask:0xf
	v_cndmask_b32_e64 v131, v107, v123, s[8:9]
	v_fmac_f32_dpp v136, v128, v186 row_ror:3 row_mask:0xf bank_mask:0xf
	v_fma_f32 v137, v211, v107, v219
	v_cndmask_b32_e64 v126, v108, v124, s[4:5]
	v_fmac_f32_dpp v137, v129, v203 row_ror:1 row_mask:0xf bank_mask:0xf
	v_cndmask_b32_e64 v127, v108, v124, s[6:7]
	v_fmac_f32_dpp v137, v130, v195 row_ror:2 row_mask:0xf bank_mask:0xf
	v_cndmask_b32_e64 v128, v108, v124, s[8:9]
	v_fmac_f32_dpp v137, v131, v187 row_ror:3 row_mask:0xf bank_mask:0xf
	v_fma_f32 v138, v212, v108, v220
	v_cndmask_b32_e64 v129, v109, v125, s[4:5]
	v_fmac_f32_dpp v138, v126, v204 row_ror:1 row_mask:0xf bank_mask:0xf
	v_cndmask_b32_e64 v130, v109, v125, s[6:7]
	v_fmac_f32_dpp v138, v127, v196 row_ror:2 row_mask:0xf bank_mask:0xf
	v_cndmask_b32_e64 v131, v109, v125, s[8:9]
	v_fmac_f32_dpp v138, v128, v188 row_ror:3 row_mask:0xf bank_mask:0xf
	v_fma_f32 v139, v213, v109, v221
	v_fmac_f32_dpp v139, v129, v205 row_ror:1 row_mask:0xf bank_mask:0xf
	v_fmac_f32_dpp v139, v130, v197 row_ror:2 row_mask:0xf bank_mask:0xf
; __device__ __forceinline__ unsigned cvt_pk_bf16(float lo, float hi) { unsigned r; asm volatile("v_cvt_pk_bf16_f32 %0, %1, %2" : "=v"(r) : "v"(lo), "v"(hi)); return r; }
; template <int K> __device__ __forceinline__ float row_ror(float v) { return __int_as_float(__builtin_amdgcn_update_dpp(0, __float_as_int(v), 0x120 + K, 0xF, 0xF, false)); }
;     EPI_ZERO_INIT
;     __device__ __forceinline__ void operator()(AccRef acc, const Unit& u, int sw) const {
;     ...
;                 for (int m = 0; m < 4; ++m) { const size_t off = (size_t)(row0 + ai * HALF + m * 16) * E + c;
;                     float y[8], x0[8];
; #pragma unroll
;                     for (int n = 0; n < 2; ++n)
; #pragma unroll
;                         for (int j = 0; j < 4; ++j) { const float cur = acc[ai][bj][m][n][j], prev = (m > 0) ? acc[ai][bj][m > 0 ? m - 1 : 0][n][j] : 0.f;
;                             const float x1 = row_ror<1>(s1 ? prev : cur), x2 = row_ror<2>(s2 ? prev : cur), x3 = row_ror<3>(s3 ? prev : cur);
;                             x0[4 * n + j] = cur;
;                             y[4 * n + j] = bb[n][j] + w0[n][j] * x3 + w1[n][j] * x2 + w2[n][j] * x1 + w3[n][j] * cur; }
;                     if (m > 0 || fr >= 3) { u32x4 w; w.x = cvt_pk_bf16(y[0], y[1]); w.y = cvt_pk_bf16(y[2], y[3]); w.z = cvt_pk_bf16(y[4], y[5]); w.w = cvt_pk_bf16(y[6], y[7]);
;                         *(u32x4*)(XC + off) = w; }
;                     if ((m == 0 && fr < 3) || (m == 3 && fr >= 13)) { u32x4 w; w.x = cvt_pk_bf16(x0[0], x0[1]); w.y = cvt_pk_bf16(x0[2], x0[3]); w.z = cvt_pk_bf16(x0[4], x0[5]); w.w = cvt_pk_bf16(x0[6], x0[7]);
;                         *(u32x4*)(XBE + off) = w; } }
	v_fmac_f32_dpp v139, v131, v189 row_ror:3 row_mask:0xf bank_mask:0xf
	v_cvt_pk_bf16_f32 v166, v132, v133
	v_cvt_pk_bf16_f32 v167, v134, v135
	v_cvt_pk_bf16_f32 v168, v136, v137
	v_cvt_pk_bf16_f32 v169, v138, v139
	v_cvt_pk_bf16_f32 v118, v114, v115
	v_cvt_pk_bf16_f32 v119, v116, v117
	v_cvt_pk_bf16_f32 v120, v106, v107
	v_cvt_pk_bf16_f32 v121, v108, v109
	global_store_dwordx4 v100, v[166:169], s[20:21]
	s_mov_b64 exec, s[8:9]
	global_store_dwordx4 v100, v[118:121], s[22:23]
	s_mov_b64 exec, -1
	s_nop 1
	v_cndmask_b32_e64 v126, v94, 0, s[4:5]
	v_cndmask_b32_e64 v127, v94, 0, s[6:7]
	v_cndmask_b32_e64 v128, v94, 0, s[8:9]
	v_fma_f32 v132, v206, v94, v214
	v_cndmask_b32_e64 v129, v95, 0, s[4:5]
	v_fmac_f32_dpp v132, v126, v198 row_ror:1 row_mask:0xf bank_mask:0xf
	v_cndmask_b32_e64 v130, v95, 0, s[6:7]
	v_fmac_f32_dpp v132, v127, v190 row_ror:2 row_mask:0xf bank_mask:0xf
	v_cndmask_b32_e64 v131, v95, 0, s[8:9]
	v_fmac_f32_dpp v132, v128, v182 row_ror:3 row_mask:0xf bank_mask:0xf
	v_fma_f32 v133, v207, v95, v215
	v_cndmask_b32_e64 v126, v96, 0, s[4:5]
	v_fmac_f32_dpp v133, v129, v199 row_ror:1 row_mask:0xf bank_mask:0xf
	v_cndmask_b32_e64 v127, v96, 0, s[6:7]
	v_fmac_f32_dpp v133, v130, v191 row_ror:2 row_mask:0xf bank_mask:0xf
	v_cndmask_b32_e64 v128, v96, 0, s[8:9]
	v_fmac_f32_dpp v133, v131, v183 row_ror:3 row_mask:0xf bank_mask:0xf
	v_fma_f32 v134, v208, v96, v216
	v_cndmask_b32_e64 v129, v97, 0, s[4:5]
	v_fmac_f32_dpp v134, v126, v200 row_ror:1 row_mask:0xf bank_mask:0xf
	v_cndmask_b32_e64 v130, v97, 0, s[6:7]
	v_fmac_f32_dpp v134, v127, v192 row_ror:2 row_mask:0xf bank_mask:0xf
	v_cndmask_b32_e64 v131, v97, 0, s[8:9]
	v_fmac_f32_dpp v134, v128, v184 row_ror:3 row_mask:0xf bank_mask:0xf
	v_fma_f32 v135, v209, v97, v217
	v_cndmask_b32_e64 v126, v90, 0, s[4:5]
	v_fmac_f32_dpp v135, v129, v201 row_ror:1 row_mask:0xf bank_mask:0xf
	v_cndmask_b32_e64 v127, v90, 0, s[6:7]
	v_fmac_f32_dpp v135, v130, v193 row_ror:2 row_mask:0xf bank_mask:0xf
	v_cndmask_b32_e64 v128, v90, 0, s[8:9]
	v_fmac_f32_dpp v135, v131, v185 row_ror:3 row_mask:0xf bank_mask:0xf
	v_fma_f32 v136, v210, v90, v218
	v_cndmask_b32_e64 v129, v91, 0, s[4:5]
	v_fmac_f32_dpp v136, v126, v202 row_ror:1 row_mask:0xf bank_mask:0xf
	v_cndmask_b32_e64 v130, v91, 0, s[6:7]
	v_fmac_f32_dpp v136, v127, v194 row_ror:2 row_mask:0xf bank_mask:0xf
	v_cndmask_b32_e64 v131, v91, 0, s[8:9]
	v_fmac_f32_dpp v136, v128, v186 row_ror:3 row_mask:0xf bank_mask:0xf
	v_fma_f32 v137, v211, v91, v219
	v_cndmask_b32_e64 v126, v92, 0, s[4:5]
	v_fmac_f32_dpp v137, v129, v203 row_ror:1 row_mask:0xf bank_mask:0xf
	v_cndmask_b32_e64 v127, v92, 0, s[6:7]
	v_fmac_f32_dpp v137, v130, v195 row_ror:2 row_mask:0xf bank_mask:0xf
	v_cndmask_b32_e64 v128, v92, 0, s[8:9]
	v_fmac_f32_dpp v137, v131, v187 row_ror:3 row_mask:0xf bank_mask:0xf
	v_fma_f32 v138, v212, v92, v220
	v_cndmask_b32_e64 v129, v93, 0, s[4:5]
	v_fmac_f32_dpp v138, v126, v204 row_ror:1 row_mask:0xf bank_mask:0xf
	v_cndmask_b32_e64 v130, v93, 0, s[6:7]
	v_fmac_f32_dpp v138, v127, v196 row_ror:2 row_mask:0xf bank_mask:0xf
	v_cndmask_b32_e64 v131, v93, 0, s[8:9]
	v_fmac_f32_dpp v138, v128, v188 row_ror:3 row_mask:0xf bank_mask:0xf
	v_fma_f32 v139, v213, v93, v221
	v_fmac_f32_dpp v139, v129, v205 row_ror:1 row_mask:0xf bank_mask:0xf
	v_fmac_f32_dpp v139, v130, v197 row_ror:2 row_mask:0xf bank_mask:0xf
	v_fmac_f32_dpp v139, v131, v189 row_ror:3 row_mask:0xf bank_mask:0xf
	v_cvt_pk_bf16_f32 v162, v132, v133
	v_cvt_pk_bf16_f32 v163, v134, v135
	v_cvt_pk_bf16_f32 v164, v136, v137
	v_cvt_pk_bf16_f32 v165, v138, v139
	v_cvt_pk_bf16_f32 v110, v94, v95
	v_cvt_pk_bf16_f32 v111, v96, v97
	v_cvt_pk_bf16_f32 v112, v90, v91
	v_cvt_pk_bf16_f32 v113, v92, v93
	s_mov_b64 exec, s[10:11]
	global_store_dwordx4 v101, v[162:165], s[20:21]
	s_not_b64 exec, exec
	global_store_dwordx4 v101, v[110:113], s[22:23]
	s_mov_b64 exec, -1
	s_nop 1
	v_cndmask_b32_e64 v126, v86, v94, s[4:5]
	v_cndmask_b32_e64 v127, v86, v94, s[6:7]
	v_cndmask_b32_e64 v128, v86, v94, s[8:9]
	v_fma_f32 v132, v206, v86, v214
	v_cndmask_b32_e64 v129, v87, v95, s[4:5]
	v_fmac_f32_dpp v132, v126, v198 row_ror:1 row_mask:0xf bank_mask:0xf
	v_cndmask_b32_e64 v130, v87, v95, s[6:7]
	v_fmac_f32_dpp v132, v127, v190 row_ror:2 row_mask:0xf bank_mask:0xf
	v_cndmask_b32_e64 v131, v87, v95, s[8:9]
	v_fmac_f32_dpp v132, v128, v182 row_ror:3 row_mask:0xf bank_mask:0xf
	v_fma_f32 v133, v207, v87, v215
	v_cndmask_b32_e64 v126, v88, v96, s[4:5]
	v_fmac_f32_dpp v133, v129, v199 row_ror:1 row_mask:0xf bank_mask:0xf
	v_cndmask_b32_e64 v127, v88, v96, s[6:7]
	v_fmac_f32_dpp v133, v130, v191 row_ror:2 row_mask:0xf bank_mask:0xf
	v_cndmask_b32_e64 v128, v88, v96, s[8:9]
	v_fmac_f32_dpp v133, v131, v183 row_ror:3 row_mask:0xf bank_mask:0xf
	v_fma_f32 v134, v208, v88, v216
	v_cndmask_b32_e64 v129, v89, v97, s[4:5]
	v_fmac_f32_dpp v134, v126, v200 row_ror:1 row_mask:0xf bank_mask:0xf
	v_cndmask_b32_e64 v130, v89, v97, s[6:7]
	v_fmac_f32_dpp v134, v127, v192 row_ror:2 row_mask:0xf bank_mask:0xf
	v_cndmask_b32_e64 v131, v89, v97, s[8:9]
	v_fmac_f32_dpp v134, v128, v184 row_ror:3 row_mask:0xf bank_mask:0xf
	v_fma_f32 v135, v209, v89, v217
	v_cndmask_b32_e64 v126, v82, v90, s[4:5]
	v_fmac_f32_dpp v135, v129, v201 row_ror:1 row_mask:0xf bank_mask:0xf
	v_cndmask_b32_e64 v127, v82, v90, s[6:7]
	v_fmac_f32_dpp v135, v130, v193 row_ror:2 row_mask:0xf bank_mask:0xf
	v_cndmask_b32_e64 v128, v82, v90, s[8:9]
	v_fmac_f32_dpp v135, v131, v185 row_ror:3 row_mask:0xf bank_mask:0xf
	v_fma_f32 v136, v210, v82, v218
	v_cndmask_b32_e64 v129, v83, v91, s[4:5]
	v_fmac_f32_dpp v136, v126, v202 row_ror:1 row_mask:0xf bank_mask:0xf
	v_cndmask_b32_e64 v130, v83, v91, s[6:7]
; __device__ __forceinline__ unsigned cvt_pk_bf16(float lo, float hi) { unsigned r; asm volatile("v_cvt_pk_bf16_f32 %0, %1, %2" : "=v"(r) : "v"(lo), "v"(hi)); return r; }
; template <int K> __device__ __forceinline__ float row_ror(float v) { return __int_as_float(__builtin_amdgcn_update_dpp(0, __float_as_int(v), 0x120 + K, 0xF, 0xF, false)); }
;     EPI_ZERO_INIT
;     __device__ __forceinline__ void operator()(AccRef acc, const Unit& u, int sw) const {
;     ...
;                 for (int m = 0; m < 4; ++m) { const size_t off = (size_t)(row0 + ai * HALF + m * 16) * E + c;
;                     float y[8], x0[8];
; #pragma unroll
;                     for (int n = 0; n < 2; ++n)
; #pragma unroll
;                         for (int j = 0; j < 4; ++j) { const float cur = acc[ai][bj][m][n][j], prev = (m > 0) ? acc[ai][bj][m > 0 ? m - 1 : 0][n][j] : 0.f;
;                             const float x1 = row_ror<1>(s1 ? prev : cur), x2 = row_ror<2>(s2 ? prev : cur), x3 = row_ror<3>(s3 ? prev : cur);
;                             x0[4 * n + j] = cur;
;                             y[4 * n + j] = bb[n][j] + w0[n][j] * x3 + w1[n][j] * x2 + w2[n][j] * x1 + w3[n][j] * cur; }
;                     if (m > 0 || fr >= 3) { u32x4 w; w.x = cvt_pk_bf16(y[0], y[1]); w.y = cvt_pk_bf16(y[2], y[3]); w.z = cvt_pk_bf16(y[4], y[5]); w.w = cvt_pk_bf16(y[6], y[7]);
;                         *(u32x4*)(XC + off) = w; }
;                     if ((m == 0 && fr < 3) || (m == 3 && fr >= 13)) { u32x4 w; w.x = cvt_pk_bf16(x0[0], x0[1]); w.y = cvt_pk_bf16(x0[2], x0[3]); w.z = cvt_pk_bf16(x0[4], x0[5]); w.w = cvt_pk_bf16(x0[6], x0[7]);
;                         *(u32x4*)(XBE + off) = w; } }
	v_fmac_f32_dpp v136, v127, v194 row_ror:2 row_mask:0xf bank_mask:0xf
	v_cndmask_b32_e64 v131, v83, v91, s[8:9]
	v_fmac_f32_dpp v136, v128, v186 row_ror:3 row_mask:0xf bank_mask:0xf
	v_fma_f32 v137, v211, v83, v219
	v_cndmask_b32_e64 v126, v84, v92, s[4:5]
	v_fmac_f32_dpp v137, v129, v203 row_ror:1 row_mask:0xf bank_mask:0xf
	v_cndmask_b32_e64 v127, v84, v92, s[6:7]
	v_fmac_f32_dpp v137, v130, v195 row_ror:2 row_mask:0xf bank_mask:0xf
	v_cndmask_b32_e64 v128, v84, v92, s[8:9]
	v_fmac_f32_dpp v137, v131, v187 row_ror:3 row_mask:0xf bank_mask:0xf
	v_fma_f32 v138, v212, v84, v220
	v_cndmask_b32_e64 v129, v85, v93, s[4:5]
	v_fmac_f32_dpp v138, v126, v204 row_ror:1 row_mask:0xf bank_mask:0xf
	v_cndmask_b32_e64 v130, v85, v93, s[6:7]
	v_fmac_f32_dpp v138, v127, v196 row_ror:2 row_mask:0xf bank_mask:0xf
	v_cndmask_b32_e64 v131, v85, v93, s[8:9]
	v_fmac_f32_dpp v138, v128, v188 row_ror:3 row_mask:0xf bank_mask:0xf
	v_fma_f32 v139, v213, v85, v221
	v_fmac_f32_dpp v139, v129, v205 row_ror:1 row_mask:0xf bank_mask:0xf
	v_fmac_f32_dpp v139, v130, v197 row_ror:2 row_mask:0xf bank_mask:0xf
	v_fmac_f32_dpp v139, v131, v189 row_ror:3 row_mask:0xf bank_mask:0xf
	v_cvt_pk_bf16_f32 v166, v132, v133
	v_cvt_pk_bf16_f32 v167, v134, v135
	v_cvt_pk_bf16_f32 v168, v136, v137
	v_cvt_pk_bf16_f32 v169, v138, v139
	global_store_dwordx4 v102, v[166:169], s[20:21]
	s_nop 1
	v_cndmask_b32_e64 v126, v78, v86, s[4:5]
	v_cndmask_b32_e64 v127, v78, v86, s[6:7]
	v_cndmask_b32_e64 v128, v78, v86, s[8:9]
	v_fma_f32 v132, v206, v78, v214
	v_cndmask_b32_e64 v129, v79, v87, s[4:5]
	v_fmac_f32_dpp v132, v126, v198 row_ror:1 row_mask:0xf bank_mask:0xf
	v_cndmask_b32_e64 v130, v79, v87, s[6:7]
	v_fmac_f32_dpp v132, v127, v190 row_ror:2 row_mask:0xf bank_mask:0xf
	v_cndmask_b32_e64 v131, v79, v87, s[8:9]
	v_fmac_f32_dpp v132, v128, v182 row_ror:3 row_mask:0xf bank_mask:0xf
	v_fma_f32 v133, v207, v79, v215
	v_cndmask_b32_e64 v126, v80, v88, s[4:5]
	v_fmac_f32_dpp v133, v129, v199 row_ror:1 row_mask:0xf bank_mask:0xf
	v_cndmask_b32_e64 v127, v80, v88, s[6:7]
	v_fmac_f32_dpp v133, v130, v191 row_ror:2 row_mask:0xf bank_mask:0xf
	v_cndmask_b32_e64 v128, v80, v88, s[8:9]
	v_fmac_f32_dpp v133, v131, v183 row_ror:3 row_mask:0xf bank_mask:0xf
	v_fma_f32 v134, v208, v80, v216
	v_cndmask_b32_e64 v129, v81, v89, s[4:5]
	v_fmac_f32_dpp v134, v126, v200 row_ror:1 row_mask:0xf bank_mask:0xf
	v_cndmask_b32_e64 v130, v81, v89, s[6:7]
	v_fmac_f32_dpp v134, v127, v192 row_ror:2 row_mask:0xf bank_mask:0xf
	v_cndmask_b32_e64 v131, v81, v89, s[8:9]
	v_fmac_f32_dpp v134, v128, v184 row_ror:3 row_mask:0xf bank_mask:0xf
	v_fma_f32 v135, v209, v81, v217
	v_cndmask_b32_e64 v126, v74, v82, s[4:5]
	v_fmac_f32_dpp v135, v129, v201 row_ror:1 row_mask:0xf bank_mask:0xf
	v_cndmask_b32_e64 v127, v74, v82, s[6:7]
	v_fmac_f32_dpp v135, v130, v193 row_ror:2 row_mask:0xf bank_mask:0xf
	v_cndmask_b32_e64 v128, v74, v82, s[8:9]
	v_fmac_f32_dpp v135, v131, v185 row_ror:3 row_mask:0xf bank_mask:0xf
	v_fma_f32 v136, v210, v74, v218
	v_cndmask_b32_e64 v129, v75, v83, s[4:5]
	v_fmac_f32_dpp v136, v126, v202 row_ror:1 row_mask:0xf bank_mask:0xf
	v_cndmask_b32_e64 v130, v75, v83, s[6:7]
	v_fmac_f32_dpp v136, v127, v194 row_ror:2 row_mask:0xf bank_mask:0xf
	v_cndmask_b32_e64 v131, v75, v83, s[8:9]
	v_fmac_f32_dpp v136, v128, v186 row_ror:3 row_mask:0xf bank_mask:0xf
	v_fma_f32 v137, v211, v75, v219
	v_cndmask_b32_e64 v126, v76, v84, s[4:5]
	v_fmac_f32_dpp v137, v129, v203 row_ror:1 row_mask:0xf bank_mask:0xf
	v_cndmask_b32_e64 v127, v76, v84, s[6:7]
	v_fmac_f32_dpp v137, v130, v195 row_ror:2 row_mask:0xf bank_mask:0xf
	v_cndmask_b32_e64 v128, v76, v84, s[8:9]
	v_fmac_f32_dpp v137, v131, v187 row_ror:3 row_mask:0xf bank_mask:0xf
	v_fma_f32 v138, v212, v76, v220
	v_cndmask_b32_e64 v129, v77, v85, s[4:5]
	v_fmac_f32_dpp v138, v126, v204 row_ror:1 row_mask:0xf bank_mask:0xf
	v_cndmask_b32_e64 v130, v77, v85, s[6:7]
	v_fmac_f32_dpp v138, v127, v196 row_ror:2 row_mask:0xf bank_mask:0xf
	v_cndmask_b32_e64 v131, v77, v85, s[8:9]
	v_fmac_f32_dpp v138, v128, v188 row_ror:3 row_mask:0xf bank_mask:0xf
	v_fma_f32 v139, v213, v77, v221
	v_fmac_f32_dpp v139, v129, v205 row_ror:1 row_mask:0xf bank_mask:0xf
	v_fmac_f32_dpp v139, v130, v197 row_ror:2 row_mask:0xf bank_mask:0xf
	v_fmac_f32_dpp v139, v131, v189 row_ror:3 row_mask:0xf bank_mask:0xf
	v_cvt_pk_bf16_f32 v162, v132, v133
	v_cvt_pk_bf16_f32 v163, v134, v135
	v_cvt_pk_bf16_f32 v164, v136, v137
	v_cvt_pk_bf16_f32 v165, v138, v139
	global_store_dwordx4 v103, v[162:165], s[20:21]
	s_nop 1
	v_cndmask_b32_e64 v126, v70, v78, s[4:5]
	v_cndmask_b32_e64 v127, v70, v78, s[6:7]
	v_cndmask_b32_e64 v128, v70, v78, s[8:9]
	v_fma_f32 v132, v206, v70, v214
	v_cndmask_b32_e64 v129, v71, v79, s[4:5]
	v_fmac_f32_dpp v132, v126, v198 row_ror:1 row_mask:0xf bank_mask:0xf
	v_cndmask_b32_e64 v130, v71, v79, s[6:7]
	v_fmac_f32_dpp v132, v127, v190 row_ror:2 row_mask:0xf bank_mask:0xf
	v_cndmask_b32_e64 v131, v71, v79, s[8:9]
	v_fmac_f32_dpp v132, v128, v182 row_ror:3 row_mask:0xf bank_mask:0xf
	v_fma_f32 v133, v207, v71, v215
	v_cndmask_b32_e64 v126, v72, v80, s[4:5]
	v_fmac_f32_dpp v133, v129, v199 row_ror:1 row_mask:0xf bank_mask:0xf
	v_cndmask_b32_e64 v127, v72, v80, s[6:7]
	v_fmac_f32_dpp v133, v130, v191 row_ror:2 row_mask:0xf bank_mask:0xf
	v_cndmask_b32_e64 v128, v72, v80, s[8:9]
	v_fmac_f32_dpp v133, v131, v183 row_ror:3 row_mask:0xf bank_mask:0xf
	v_fma_f32 v134, v208, v72, v216
	v_cndmask_b32_e64 v129, v73, v81, s[4:5]
	v_fmac_f32_dpp v134, v126, v200 row_ror:1 row_mask:0xf bank_mask:0xf
	v_cndmask_b32_e64 v130, v73, v81, s[6:7]
	v_fmac_f32_dpp v134, v127, v192 row_ror:2 row_mask:0xf bank_mask:0xf
; #define LAS __attribute__((address_space(3)))
; __device__ __forceinline__ unsigned cvt_pk_bf16(float lo, float hi) { unsigned r; asm volatile("v_cvt_pk_bf16_f32 %0, %1, %2" : "=v"(r) : "v"(lo), "v"(hi)); return r; }
; template <int K> __device__ __forceinline__ float row_ror(float v) { return __int_as_float(__builtin_amdgcn_update_dpp(0, __float_as_int(v), 0x120 + K, 0xF, 0xF, false)); }
;     EPI_ZERO_INIT
;     __device__ __forceinline__ void operator()(AccRef acc, const Unit& u, int sw) const {
;     ...
;         for (int bj = 0; bj < 2; ++bj) { const int c = col0 + bj * HALF;
;             f32x4 w0[2], w1[2], w2[2], w3[2], bb[2];
; #pragma unroll
;             for (int n = 0; n < 2; ++n) { const int cc = bj * HALF + wc * 32 + 8 * fq + 4 * n;
;                 w0[n] = *(const LAS f32x4*)(cl + 0 * 256 + cc); w1[n] = *(const LAS f32x4*)(cl + 1 * 256 + cc); w2[n] = *(const LAS f32x4*)(cl + 2 * 256 + cc);
;                 w3[n] = *(const LAS f32x4*)(cl + 3 * 256 + cc); bb[n] = *(const LAS f32x4*)(cl + 4 * 256 + cc); }
; #pragma unroll
;             for (int ai = 0; ai < 2; ++ai)
; #pragma unroll
;                 for (int m = 0; m < 4; ++m) { const size_t off = (size_t)(row0 + ai * HALF + m * 16) * E + c;
;                     float y[8], x0[8];
; #pragma unroll
;                     for (int n = 0; n < 2; ++n)
; #pragma unroll
;                         for (int j = 0; j < 4; ++j) { const float cur = acc[ai][bj][m][n][j], prev = (m > 0) ? acc[ai][bj][m > 0 ? m - 1 : 0][n][j] : 0.f;
;                             const float x1 = row_ror<1>(s1 ? prev : cur), x2 = row_ror<2>(s2 ? prev : cur), x3 = row_ror<3>(s3 ? prev : cur);
;                             x0[4 * n + j] = cur;
;                             y[4 * n + j] = bb[n][j] + w0[n][j] * x3 + w1[n][j] * x2 + w2[n][j] * x1 + w3[n][j] * cur; }
;                     if (m > 0 || fr >= 3) { u32x4 w; w.x = cvt_pk_bf16(y[0], y[1]); w.y = cvt_pk_bf16(y[2], y[3]); w.z = cvt_pk_bf16(y[4], y[5]); w.w = cvt_pk_bf16(y[6], y[7]);
;                         *(u32x4*)(XC + off) = w; }
;                     if ((m == 0 && fr < 3) || (m == 3 && fr >= 13)) { u32x4 w; w.x = cvt_pk_bf16(x0[0], x0[1]); w.y = cvt_pk_bf16(x0[2], x0[3]); w.z = cvt_pk_bf16(x0[4], x0[5]); w.w = cvt_pk_bf16(x0[6], x0[7]);
;                         *(u32x4*)(XBE + off) = w; } }
	v_cndmask_b32_e64 v131, v73, v81, s[8:9]
	v_fmac_f32_dpp v134, v128, v184 row_ror:3 row_mask:0xf bank_mask:0xf
	v_fma_f32 v135, v209, v73, v217
	v_cndmask_b32_e64 v126, v66, v74, s[4:5]
	v_fmac_f32_dpp v135, v129, v201 row_ror:1 row_mask:0xf bank_mask:0xf
	v_cndmask_b32_e64 v127, v66, v74, s[6:7]
	v_fmac_f32_dpp v135, v130, v193 row_ror:2 row_mask:0xf bank_mask:0xf
	v_cndmask_b32_e64 v128, v66, v74, s[8:9]
	v_fmac_f32_dpp v135, v131, v185 row_ror:3 row_mask:0xf bank_mask:0xf
	v_fma_f32 v136, v210, v66, v218
	v_cndmask_b32_e64 v129, v67, v75, s[4:5]
	v_fmac_f32_dpp v136, v126, v202 row_ror:1 row_mask:0xf bank_mask:0xf
	v_cndmask_b32_e64 v130, v67, v75, s[6:7]
	v_fmac_f32_dpp v136, v127, v194 row_ror:2 row_mask:0xf bank_mask:0xf
	v_cndmask_b32_e64 v131, v67, v75, s[8:9]
	v_fmac_f32_dpp v136, v128, v186 row_ror:3 row_mask:0xf bank_mask:0xf
	v_fma_f32 v137, v211, v67, v219
	v_cndmask_b32_e64 v126, v68, v76, s[4:5]
	v_fmac_f32_dpp v137, v129, v203 row_ror:1 row_mask:0xf bank_mask:0xf
	v_cndmask_b32_e64 v127, v68, v76, s[6:7]
	v_fmac_f32_dpp v137, v130, v195 row_ror:2 row_mask:0xf bank_mask:0xf
	v_cndmask_b32_e64 v128, v68, v76, s[8:9]
	v_fmac_f32_dpp v137, v131, v187 row_ror:3 row_mask:0xf bank_mask:0xf
	v_fma_f32 v138, v212, v68, v220
	v_cndmask_b32_e64 v129, v69, v77, s[4:5]
	v_fmac_f32_dpp v138, v126, v204 row_ror:1 row_mask:0xf bank_mask:0xf
	v_cndmask_b32_e64 v130, v69, v77, s[6:7]
	v_fmac_f32_dpp v138, v127, v196 row_ror:2 row_mask:0xf bank_mask:0xf
	v_cndmask_b32_e64 v131, v69, v77, s[8:9]
	v_fmac_f32_dpp v138, v128, v188 row_ror:3 row_mask:0xf bank_mask:0xf
	v_fma_f32 v139, v213, v69, v221
	v_fmac_f32_dpp v139, v129, v205 row_ror:1 row_mask:0xf bank_mask:0xf
	v_fmac_f32_dpp v139, v130, v197 row_ror:2 row_mask:0xf bank_mask:0xf
	v_fmac_f32_dpp v139, v131, v189 row_ror:3 row_mask:0xf bank_mask:0xf
	v_cvt_pk_bf16_f32 v166, v132, v133
	v_cvt_pk_bf16_f32 v167, v134, v135
	v_cvt_pk_bf16_f32 v168, v136, v137
	v_cvt_pk_bf16_f32 v169, v138, v139
	v_cvt_pk_bf16_f32 v118, v70, v71
	v_cvt_pk_bf16_f32 v119, v72, v73
	v_cvt_pk_bf16_f32 v120, v66, v67
	v_cvt_pk_bf16_f32 v121, v68, v69
	global_store_dwordx4 v104, v[166:169], s[20:21]
	s_mov_b64 exec, s[8:9]
	global_store_dwordx4 v104, v[118:121], s[22:23]
	s_mov_b64 exec, -1
	s_nop 1
	ds_read_b128 v[182:185], v224 offset:512
	ds_read_b128 v[186:189], v224 offset:528
	ds_read_b128 v[190:193], v224 offset:1536
	ds_read_b128 v[194:197], v224 offset:1552
	ds_read_b128 v[198:201], v224 offset:2560
	ds_read_b128 v[202:205], v224 offset:2576
	ds_read_b128 v[206:209], v224 offset:3584
	ds_read_b128 v[210:213], v224 offset:3600
	ds_read_b128 v[214:217], v224 offset:4608
	ds_read_b128 v[218:221], v224 offset:4624
	s_waitcnt lgkmcnt(0)
	v_cndmask_b32_e64 v126, v62, 0, s[4:5]
	v_cndmask_b32_e64 v127, v62, 0, s[6:7]
	v_cndmask_b32_e64 v128, v62, 0, s[8:9]
	v_fma_f32 v132, v206, v62, v214
	v_cndmask_b32_e64 v129, v63, 0, s[4:5]
	v_fmac_f32_dpp v132, v126, v198 row_ror:1 row_mask:0xf bank_mask:0xf
	v_cndmask_b32_e64 v130, v63, 0, s[6:7]
	v_fmac_f32_dpp v132, v127, v190 row_ror:2 row_mask:0xf bank_mask:0xf
	v_cndmask_b32_e64 v131, v63, 0, s[8:9]
	v_fmac_f32_dpp v132, v128, v182 row_ror:3 row_mask:0xf bank_mask:0xf
	v_fma_f32 v133, v207, v63, v215
	v_cndmask_b32_e64 v126, v64, 0, s[4:5]
	v_fmac_f32_dpp v133, v129, v199 row_ror:1 row_mask:0xf bank_mask:0xf
	v_cndmask_b32_e64 v127, v64, 0, s[6:7]
	v_fmac_f32_dpp v133, v130, v191 row_ror:2 row_mask:0xf bank_mask:0xf
	v_cndmask_b32_e64 v128, v64, 0, s[8:9]
	v_fmac_f32_dpp v133, v131, v183 row_ror:3 row_mask:0xf bank_mask:0xf
	v_fma_f32 v134, v208, v64, v216
	v_cndmask_b32_e64 v129, v65, 0, s[4:5]
	v_fmac_f32_dpp v134, v126, v200 row_ror:1 row_mask:0xf bank_mask:0xf
	v_cndmask_b32_e64 v130, v65, 0, s[6:7]
	v_fmac_f32_dpp v134, v127, v192 row_ror:2 row_mask:0xf bank_mask:0xf
	v_cndmask_b32_e64 v131, v65, 0, s[8:9]
	v_fmac_f32_dpp v134, v128, v184 row_ror:3 row_mask:0xf bank_mask:0xf
	v_fma_f32 v135, v209, v65, v217
	v_cndmask_b32_e64 v126, v58, 0, s[4:5]
	v_fmac_f32_dpp v135, v129, v201 row_ror:1 row_mask:0xf bank_mask:0xf
	v_cndmask_b32_e64 v127, v58, 0, s[6:7]
	v_fmac_f32_dpp v135, v130, v193 row_ror:2 row_mask:0xf bank_mask:0xf
	v_cndmask_b32_e64 v128, v58, 0, s[8:9]
	v_fmac_f32_dpp v135, v131, v185 row_ror:3 row_mask:0xf bank_mask:0xf
	v_fma_f32 v136, v210, v58, v218
	v_cndmask_b32_e64 v129, v59, 0, s[4:5]
	v_fmac_f32_dpp v136, v126, v202 row_ror:1 row_mask:0xf bank_mask:0xf
	v_cndmask_b32_e64 v130, v59, 0, s[6:7]
	v_fmac_f32_dpp v136, v127, v194 row_ror:2 row_mask:0xf bank_mask:0xf
	v_cndmask_b32_e64 v131, v59, 0, s[8:9]
	v_fmac_f32_dpp v136, v128, v186 row_ror:3 row_mask:0xf bank_mask:0xf
	v_fma_f32 v137, v211, v59, v219
	v_cndmask_b32_e64 v126, v60, 0, s[4:5]
	v_fmac_f32_dpp v137, v129, v203 row_ror:1 row_mask:0xf bank_mask:0xf
	v_cndmask_b32_e64 v127, v60, 0, s[6:7]
	v_fmac_f32_dpp v137, v130, v195 row_ror:2 row_mask:0xf bank_mask:0xf
	v_cndmask_b32_e64 v128, v60, 0, s[8:9]
	v_fmac_f32_dpp v137, v131, v187 row_ror:3 row_mask:0xf bank_mask:0xf
	v_fma_f32 v138, v212, v60, v220
	v_cndmask_b32_e64 v129, v61, 0, s[4:5]
	v_fmac_f32_dpp v138, v126, v204 row_ror:1 row_mask:0xf bank_mask:0xf
	v_cndmask_b32_e64 v130, v61, 0, s[6:7]
	v_fmac_f32_dpp v138, v127, v196 row_ror:2 row_mask:0xf bank_mask:0xf
	v_cndmask_b32_e64 v131, v61, 0, s[8:9]
	v_fmac_f32_dpp v138, v128, v188 row_ror:3 row_mask:0xf bank_mask:0xf
	v_fma_f32 v139, v213, v61, v221
	v_fmac_f32_dpp v139, v129, v205 row_ror:1 row_mask:0xf bank_mask:0xf
	v_fmac_f32_dpp v139, v130, v197 row_ror:2 row_mask:0xf bank_mask:0xf
	v_fmac_f32_dpp v139, v131, v189 row_ror:3 row_mask:0xf bank_mask:0xf
	v_cvt_pk_bf16_f32 v162, v132, v133
; __device__ __forceinline__ unsigned cvt_pk_bf16(float lo, float hi) { unsigned r; asm volatile("v_cvt_pk_bf16_f32 %0, %1, %2" : "=v"(r) : "v"(lo), "v"(hi)); return r; }
; template <int K> __device__ __forceinline__ float row_ror(float v) { return __int_as_float(__builtin_amdgcn_update_dpp(0, __float_as_int(v), 0x120 + K, 0xF, 0xF, false)); }
;     EPI_ZERO_INIT
;     __device__ __forceinline__ void operator()(AccRef acc, const Unit& u, int sw) const {
;     ...
;                 for (int m = 0; m < 4; ++m) { const size_t off = (size_t)(row0 + ai * HALF + m * 16) * E + c;
;                     float y[8], x0[8];
; #pragma unroll
;                     for (int n = 0; n < 2; ++n)
; #pragma unroll
;                         for (int j = 0; j < 4; ++j) { const float cur = acc[ai][bj][m][n][j], prev = (m > 0) ? acc[ai][bj][m > 0 ? m - 1 : 0][n][j] : 0.f;
;                             const float x1 = row_ror<1>(s1 ? prev : cur), x2 = row_ror<2>(s2 ? prev : cur), x3 = row_ror<3>(s3 ? prev : cur);
;                             x0[4 * n + j] = cur;
;                             y[4 * n + j] = bb[n][j] + w0[n][j] * x3 + w1[n][j] * x2 + w2[n][j] * x1 + w3[n][j] * cur; }
;                     if (m > 0 || fr >= 3) { u32x4 w; w.x = cvt_pk_bf16(y[0], y[1]); w.y = cvt_pk_bf16(y[2], y[3]); w.z = cvt_pk_bf16(y[4], y[5]); w.w = cvt_pk_bf16(y[6], y[7]);
;                         *(u32x4*)(XC + off) = w; }
;                     if ((m == 0 && fr < 3) || (m == 3 && fr >= 13)) { u32x4 w; w.x = cvt_pk_bf16(x0[0], x0[1]); w.y = cvt_pk_bf16(x0[2], x0[3]); w.z = cvt_pk_bf16(x0[4], x0[5]); w.w = cvt_pk_bf16(x0[6], x0[7]);
;                         *(u32x4*)(XBE + off) = w; } }
	v_cvt_pk_bf16_f32 v163, v134, v135
	v_cvt_pk_bf16_f32 v164, v136, v137
	v_cvt_pk_bf16_f32 v165, v138, v139
	v_cvt_pk_bf16_f32 v110, v62, v63
	v_cvt_pk_bf16_f32 v111, v64, v65
	v_cvt_pk_bf16_f32 v112, v58, v59
	v_cvt_pk_bf16_f32 v113, v60, v61
	s_mov_b64 exec, s[10:11]
	global_store_dwordx4 v226, v[162:165], s[20:21] offset:256
	s_not_b64 exec, exec
	global_store_dwordx4 v226, v[110:113], s[22:23] offset:256
	s_mov_b64 exec, -1
	s_nop 1
	v_cndmask_b32_e64 v126, v54, v62, s[4:5]
	v_cndmask_b32_e64 v127, v54, v62, s[6:7]
	v_cndmask_b32_e64 v128, v54, v62, s[8:9]
	v_fma_f32 v132, v206, v54, v214
	v_cndmask_b32_e64 v129, v55, v63, s[4:5]
	v_fmac_f32_dpp v132, v126, v198 row_ror:1 row_mask:0xf bank_mask:0xf
	v_cndmask_b32_e64 v130, v55, v63, s[6:7]
	v_fmac_f32_dpp v132, v127, v190 row_ror:2 row_mask:0xf bank_mask:0xf
	v_cndmask_b32_e64 v131, v55, v63, s[8:9]
	v_fmac_f32_dpp v132, v128, v182 row_ror:3 row_mask:0xf bank_mask:0xf
	v_fma_f32 v133, v207, v55, v215
	v_cndmask_b32_e64 v126, v56, v64, s[4:5]
	v_fmac_f32_dpp v133, v129, v199 row_ror:1 row_mask:0xf bank_mask:0xf
	v_cndmask_b32_e64 v127, v56, v64, s[6:7]
	v_fmac_f32_dpp v133, v130, v191 row_ror:2 row_mask:0xf bank_mask:0xf
	v_cndmask_b32_e64 v128, v56, v64, s[8:9]
	v_fmac_f32_dpp v133, v131, v183 row_ror:3 row_mask:0xf bank_mask:0xf
	v_fma_f32 v134, v208, v56, v216
	v_cndmask_b32_e64 v129, v57, v65, s[4:5]
	v_fmac_f32_dpp v134, v126, v200 row_ror:1 row_mask:0xf bank_mask:0xf
	v_cndmask_b32_e64 v130, v57, v65, s[6:7]
	v_fmac_f32_dpp v134, v127, v192 row_ror:2 row_mask:0xf bank_mask:0xf
	v_cndmask_b32_e64 v131, v57, v65, s[8:9]
	v_fmac_f32_dpp v134, v128, v184 row_ror:3 row_mask:0xf bank_mask:0xf
	v_fma_f32 v135, v209, v57, v217
	v_cndmask_b32_e64 v126, v50, v58, s[4:5]
	v_fmac_f32_dpp v135, v129, v201 row_ror:1 row_mask:0xf bank_mask:0xf
	v_cndmask_b32_e64 v127, v50, v58, s[6:7]
	v_fmac_f32_dpp v135, v130, v193 row_ror:2 row_mask:0xf bank_mask:0xf
	v_cndmask_b32_e64 v128, v50, v58, s[8:9]
	v_fmac_f32_dpp v135, v131, v185 row_ror:3 row_mask:0xf bank_mask:0xf
	v_fma_f32 v136, v210, v50, v218
	v_cndmask_b32_e64 v129, v51, v59, s[4:5]
	v_fmac_f32_dpp v136, v126, v202 row_ror:1 row_mask:0xf bank_mask:0xf
	v_cndmask_b32_e64 v130, v51, v59, s[6:7]
	v_fmac_f32_dpp v136, v127, v194 row_ror:2 row_mask:0xf bank_mask:0xf
	v_cndmask_b32_e64 v131, v51, v59, s[8:9]
	v_fmac_f32_dpp v136, v128, v186 row_ror:3 row_mask:0xf bank_mask:0xf
	v_fma_f32 v137, v211, v51, v219
	v_cndmask_b32_e64 v126, v52, v60, s[4:5]
	v_fmac_f32_dpp v137, v129, v203 row_ror:1 row_mask:0xf bank_mask:0xf
	v_cndmask_b32_e64 v127, v52, v60, s[6:7]
	v_fmac_f32_dpp v137, v130, v195 row_ror:2 row_mask:0xf bank_mask:0xf
	v_cndmask_b32_e64 v128, v52, v60, s[8:9]
	v_fmac_f32_dpp v137, v131, v187 row_ror:3 row_mask:0xf bank_mask:0xf
	v_fma_f32 v138, v212, v52, v220
	v_cndmask_b32_e64 v129, v53, v61, s[4:5]
	v_fmac_f32_dpp v138, v126, v204 row_ror:1 row_mask:0xf bank_mask:0xf
	v_cndmask_b32_e64 v130, v53, v61, s[6:7]
	v_fmac_f32_dpp v138, v127, v196 row_ror:2 row_mask:0xf bank_mask:0xf
	v_cndmask_b32_e64 v131, v53, v61, s[8:9]
	v_fmac_f32_dpp v138, v128, v188 row_ror:3 row_mask:0xf bank_mask:0xf
	v_fma_f32 v139, v213, v53, v221
	v_fmac_f32_dpp v139, v129, v205 row_ror:1 row_mask:0xf bank_mask:0xf
	v_fmac_f32_dpp v139, v130, v197 row_ror:2 row_mask:0xf bank_mask:0xf
	v_fmac_f32_dpp v139, v131, v189 row_ror:3 row_mask:0xf bank_mask:0xf
	v_cvt_pk_bf16_f32 v166, v132, v133
	v_cvt_pk_bf16_f32 v167, v134, v135
	v_cvt_pk_bf16_f32 v168, v136, v137
	v_cvt_pk_bf16_f32 v169, v138, v139
	global_store_dwordx4 v98, v[166:169], s[20:21] offset:256
	s_nop 1
	v_cndmask_b32_e64 v126, v46, v54, s[4:5]
	v_cndmask_b32_e64 v127, v46, v54, s[6:7]
	v_cndmask_b32_e64 v128, v46, v54, s[8:9]
	v_fma_f32 v132, v206, v46, v214
	v_cndmask_b32_e64 v129, v47, v55, s[4:5]
	v_fmac_f32_dpp v132, v126, v198 row_ror:1 row_mask:0xf bank_mask:0xf
	v_cndmask_b32_e64 v130, v47, v55, s[6:7]
	v_fmac_f32_dpp v132, v127, v190 row_ror:2 row_mask:0xf bank_mask:0xf
	v_cndmask_b32_e64 v131, v47, v55, s[8:9]
	v_fmac_f32_dpp v132, v128, v182 row_ror:3 row_mask:0xf bank_mask:0xf
	v_fma_f32 v133, v207, v47, v215
	v_cndmask_b32_e64 v126, v48, v56, s[4:5]
	v_fmac_f32_dpp v133, v129, v199 row_ror:1 row_mask:0xf bank_mask:0xf
	v_cndmask_b32_e64 v127, v48, v56, s[6:7]
	v_fmac_f32_dpp v133, v130, v191 row_ror:2 row_mask:0xf bank_mask:0xf
	v_cndmask_b32_e64 v128, v48, v56, s[8:9]
	v_fmac_f32_dpp v133, v131, v183 row_ror:3 row_mask:0xf bank_mask:0xf
	v_fma_f32 v134, v208, v48, v216
	v_cndmask_b32_e64 v129, v49, v57, s[4:5]
	v_fmac_f32_dpp v134, v126, v200 row_ror:1 row_mask:0xf bank_mask:0xf
	v_cndmask_b32_e64 v130, v49, v57, s[6:7]
	v_fmac_f32_dpp v134, v127, v192 row_ror:2 row_mask:0xf bank_mask:0xf
	v_cndmask_b32_e64 v131, v49, v57, s[8:9]
	v_fmac_f32_dpp v134, v128, v184 row_ror:3 row_mask:0xf bank_mask:0xf
	v_fma_f32 v135, v209, v49, v217
	v_cndmask_b32_e64 v126, v42, v50, s[4:5]
	v_fmac_f32_dpp v135, v129, v201 row_ror:1 row_mask:0xf bank_mask:0xf
	v_cndmask_b32_e64 v127, v42, v50, s[6:7]
	v_fmac_f32_dpp v135, v130, v193 row_ror:2 row_mask:0xf bank_mask:0xf
	v_cndmask_b32_e64 v128, v42, v50, s[8:9]
	v_fmac_f32_dpp v135, v131, v185 row_ror:3 row_mask:0xf bank_mask:0xf
	v_fma_f32 v136, v210, v42, v218
	v_cndmask_b32_e64 v129, v43, v51, s[4:5]
	v_fmac_f32_dpp v136, v126, v202 row_ror:1 row_mask:0xf bank_mask:0xf
	v_cndmask_b32_e64 v130, v43, v51, s[6:7]
	v_fmac_f32_dpp v136, v127, v194 row_ror:2 row_mask:0xf bank_mask:0xf
	v_cndmask_b32_e64 v131, v43, v51, s[8:9]
	v_fmac_f32_dpp v136, v128, v186 row_ror:3 row_mask:0xf bank_mask:0xf
	v_fma_f32 v137, v211, v43, v219
	v_cndmask_b32_e64 v126, v44, v52, s[4:5]
; __device__ __forceinline__ unsigned cvt_pk_bf16(float lo, float hi) { unsigned r; asm volatile("v_cvt_pk_bf16_f32 %0, %1, %2" : "=v"(r) : "v"(lo), "v"(hi)); return r; }
; template <int K> __device__ __forceinline__ float row_ror(float v) { return __int_as_float(__builtin_amdgcn_update_dpp(0, __float_as_int(v), 0x120 + K, 0xF, 0xF, false)); }
;     EPI_ZERO_INIT
;     __device__ __forceinline__ void operator()(AccRef acc, const Unit& u, int sw) const {
;     ...
;                 for (int m = 0; m < 4; ++m) { const size_t off = (size_t)(row0 + ai * HALF + m * 16) * E + c;
;                     float y[8], x0[8];
; #pragma unroll
;                     for (int n = 0; n < 2; ++n)
; #pragma unroll
;                         for (int j = 0; j < 4; ++j) { const float cur = acc[ai][bj][m][n][j], prev = (m > 0) ? acc[ai][bj][m > 0 ? m - 1 : 0][n][j] : 0.f;
;                             const float x1 = row_ror<1>(s1 ? prev : cur), x2 = row_ror<2>(s2 ? prev : cur), x3 = row_ror<3>(s3 ? prev : cur);
;                             x0[4 * n + j] = cur;
;                             y[4 * n + j] = bb[n][j] + w0[n][j] * x3 + w1[n][j] * x2 + w2[n][j] * x1 + w3[n][j] * cur; }
;                     if (m > 0 || fr >= 3) { u32x4 w; w.x = cvt_pk_bf16(y[0], y[1]); w.y = cvt_pk_bf16(y[2], y[3]); w.z = cvt_pk_bf16(y[4], y[5]); w.w = cvt_pk_bf16(y[6], y[7]);
;                         *(u32x4*)(XC + off) = w; }
;                     if ((m == 0 && fr < 3) || (m == 3 && fr >= 13)) { u32x4 w; w.x = cvt_pk_bf16(x0[0], x0[1]); w.y = cvt_pk_bf16(x0[2], x0[3]); w.z = cvt_pk_bf16(x0[4], x0[5]); w.w = cvt_pk_bf16(x0[6], x0[7]);
;                         *(u32x4*)(XBE + off) = w; } }
	v_fmac_f32_dpp v137, v129, v203 row_ror:1 row_mask:0xf bank_mask:0xf
	v_cndmask_b32_e64 v127, v44, v52, s[6:7]
	v_fmac_f32_dpp v137, v130, v195 row_ror:2 row_mask:0xf bank_mask:0xf
	v_cndmask_b32_e64 v128, v44, v52, s[8:9]
	v_fmac_f32_dpp v137, v131, v187 row_ror:3 row_mask:0xf bank_mask:0xf
	v_fma_f32 v138, v212, v44, v220
	v_cndmask_b32_e64 v129, v45, v53, s[4:5]
	v_fmac_f32_dpp v138, v126, v204 row_ror:1 row_mask:0xf bank_mask:0xf
	v_cndmask_b32_e64 v130, v45, v53, s[6:7]
	v_fmac_f32_dpp v138, v127, v196 row_ror:2 row_mask:0xf bank_mask:0xf
	v_cndmask_b32_e64 v131, v45, v53, s[8:9]
	v_fmac_f32_dpp v138, v128, v188 row_ror:3 row_mask:0xf bank_mask:0xf
	v_fma_f32 v139, v213, v45, v221
	v_fmac_f32_dpp v139, v129, v205 row_ror:1 row_mask:0xf bank_mask:0xf
	v_fmac_f32_dpp v139, v130, v197 row_ror:2 row_mask:0xf bank_mask:0xf
	v_fmac_f32_dpp v139, v131, v189 row_ror:3 row_mask:0xf bank_mask:0xf
	v_cvt_pk_bf16_f32 v162, v132, v133
	v_cvt_pk_bf16_f32 v163, v134, v135
	v_cvt_pk_bf16_f32 v164, v136, v137
	v_cvt_pk_bf16_f32 v165, v138, v139
	global_store_dwordx4 v99, v[162:165], s[20:21] offset:256
	s_nop 1
	v_cndmask_b32_e64 v126, v38, v46, s[4:5]
	v_cndmask_b32_e64 v127, v38, v46, s[6:7]
	v_cndmask_b32_e64 v128, v38, v46, s[8:9]
	v_fma_f32 v132, v206, v38, v214
	v_cndmask_b32_e64 v129, v39, v47, s[4:5]
	v_fmac_f32_dpp v132, v126, v198 row_ror:1 row_mask:0xf bank_mask:0xf
	v_cndmask_b32_e64 v130, v39, v47, s[6:7]
	v_fmac_f32_dpp v132, v127, v190 row_ror:2 row_mask:0xf bank_mask:0xf
	v_cndmask_b32_e64 v131, v39, v47, s[8:9]
	v_fmac_f32_dpp v132, v128, v182 row_ror:3 row_mask:0xf bank_mask:0xf
	v_fma_f32 v133, v207, v39, v215
	v_cndmask_b32_e64 v126, v40, v48, s[4:5]
	v_fmac_f32_dpp v133, v129, v199 row_ror:1 row_mask:0xf bank_mask:0xf
	v_cndmask_b32_e64 v127, v40, v48, s[6:7]
	v_fmac_f32_dpp v133, v130, v191 row_ror:2 row_mask:0xf bank_mask:0xf
	v_cndmask_b32_e64 v128, v40, v48, s[8:9]
	v_fmac_f32_dpp v133, v131, v183 row_ror:3 row_mask:0xf bank_mask:0xf
	v_fma_f32 v134, v208, v40, v216
	v_cndmask_b32_e64 v129, v41, v49, s[4:5]
	v_fmac_f32_dpp v134, v126, v200 row_ror:1 row_mask:0xf bank_mask:0xf
	v_cndmask_b32_e64 v130, v41, v49, s[6:7]
	v_fmac_f32_dpp v134, v127, v192 row_ror:2 row_mask:0xf bank_mask:0xf
	v_cndmask_b32_e64 v131, v41, v49, s[8:9]
	v_fmac_f32_dpp v134, v128, v184 row_ror:3 row_mask:0xf bank_mask:0xf
	v_fma_f32 v135, v209, v41, v217
	v_cndmask_b32_e64 v126, v34, v42, s[4:5]
	v_fmac_f32_dpp v135, v129, v201 row_ror:1 row_mask:0xf bank_mask:0xf
	v_cndmask_b32_e64 v127, v34, v42, s[6:7]
	v_fmac_f32_dpp v135, v130, v193 row_ror:2 row_mask:0xf bank_mask:0xf
	v_cndmask_b32_e64 v128, v34, v42, s[8:9]
	v_fmac_f32_dpp v135, v131, v185 row_ror:3 row_mask:0xf bank_mask:0xf
	v_fma_f32 v136, v210, v34, v218
	v_cndmask_b32_e64 v129, v35, v43, s[4:5]
	v_fmac_f32_dpp v136, v126, v202 row_ror:1 row_mask:0xf bank_mask:0xf
	v_cndmask_b32_e64 v130, v35, v43, s[6:7]
	v_fmac_f32_dpp v136, v127, v194 row_ror:2 row_mask:0xf bank_mask:0xf
	v_cndmask_b32_e64 v131, v35, v43, s[8:9]
	v_fmac_f32_dpp v136, v128, v186 row_ror:3 row_mask:0xf bank_mask:0xf
	v_fma_f32 v137, v211, v35, v219
	v_cndmask_b32_e64 v126, v36, v44, s[4:5]
	v_fmac_f32_dpp v137, v129, v203 row_ror:1 row_mask:0xf bank_mask:0xf
	v_cndmask_b32_e64 v127, v36, v44, s[6:7]
	v_fmac_f32_dpp v137, v130, v195 row_ror:2 row_mask:0xf bank_mask:0xf
	v_cndmask_b32_e64 v128, v36, v44, s[8:9]
	v_fmac_f32_dpp v137, v131, v187 row_ror:3 row_mask:0xf bank_mask:0xf
	v_fma_f32 v138, v212, v36, v220
	v_cndmask_b32_e64 v129, v37, v45, s[4:5]
	v_fmac_f32_dpp v138, v126, v204 row_ror:1 row_mask:0xf bank_mask:0xf
	v_cndmask_b32_e64 v130, v37, v45, s[6:7]
	v_fmac_f32_dpp v138, v127, v196 row_ror:2 row_mask:0xf bank_mask:0xf
	v_cndmask_b32_e64 v131, v37, v45, s[8:9]
	v_fmac_f32_dpp v138, v128, v188 row_ror:3 row_mask:0xf bank_mask:0xf
	v_fma_f32 v139, v213, v37, v221
	v_fmac_f32_dpp v139, v129, v205 row_ror:1 row_mask:0xf bank_mask:0xf
	v_fmac_f32_dpp v139, v130, v197 row_ror:2 row_mask:0xf bank_mask:0xf
	v_fmac_f32_dpp v139, v131, v189 row_ror:3 row_mask:0xf bank_mask:0xf
	v_cvt_pk_bf16_f32 v166, v132, v133
	v_cvt_pk_bf16_f32 v167, v134, v135
	v_cvt_pk_bf16_f32 v168, v136, v137
	v_cvt_pk_bf16_f32 v169, v138, v139
	v_cvt_pk_bf16_f32 v118, v38, v39
	v_cvt_pk_bf16_f32 v119, v40, v41
	v_cvt_pk_bf16_f32 v120, v34, v35
	v_cvt_pk_bf16_f32 v121, v36, v37
	global_store_dwordx4 v100, v[166:169], s[20:21] offset:256
	s_mov_b64 exec, s[8:9]
	global_store_dwordx4 v100, v[118:121], s[22:23] offset:256
	s_mov_b64 exec, -1
	s_nop 1
	v_cndmask_b32_e64 v126, v30, 0, s[4:5]
	v_cndmask_b32_e64 v127, v30, 0, s[6:7]
	v_cndmask_b32_e64 v128, v30, 0, s[8:9]
	v_fma_f32 v132, v206, v30, v214
	v_cndmask_b32_e64 v129, v31, 0, s[4:5]
	v_fmac_f32_dpp v132, v126, v198 row_ror:1 row_mask:0xf bank_mask:0xf
	v_cndmask_b32_e64 v130, v31, 0, s[6:7]
	v_fmac_f32_dpp v132, v127, v190 row_ror:2 row_mask:0xf bank_mask:0xf
	v_cndmask_b32_e64 v131, v31, 0, s[8:9]
	v_fmac_f32_dpp v132, v128, v182 row_ror:3 row_mask:0xf bank_mask:0xf
	v_fma_f32 v133, v207, v31, v215
	v_cndmask_b32_e64 v126, v32, 0, s[4:5]
	v_fmac_f32_dpp v133, v129, v199 row_ror:1 row_mask:0xf bank_mask:0xf
	v_cndmask_b32_e64 v127, v32, 0, s[6:7]
	v_fmac_f32_dpp v133, v130, v191 row_ror:2 row_mask:0xf bank_mask:0xf
	v_cndmask_b32_e64 v128, v32, 0, s[8:9]
	v_fmac_f32_dpp v133, v131, v183 row_ror:3 row_mask:0xf bank_mask:0xf
	v_fma_f32 v134, v208, v32, v216
	v_cndmask_b32_e64 v129, v33, 0, s[4:5]
	v_fmac_f32_dpp v134, v126, v200 row_ror:1 row_mask:0xf bank_mask:0xf
	v_cndmask_b32_e64 v130, v33, 0, s[6:7]
	v_fmac_f32_dpp v134, v127, v192 row_ror:2 row_mask:0xf bank_mask:0xf
; __device__ __forceinline__ unsigned cvt_pk_bf16(float lo, float hi) { unsigned r; asm volatile("v_cvt_pk_bf16_f32 %0, %1, %2" : "=v"(r) : "v"(lo), "v"(hi)); return r; }
; template <int K> __device__ __forceinline__ float row_ror(float v) { return __int_as_float(__builtin_amdgcn_update_dpp(0, __float_as_int(v), 0x120 + K, 0xF, 0xF, false)); }
;     EPI_ZERO_INIT
;     __device__ __forceinline__ void operator()(AccRef acc, const Unit& u, int sw) const {
;     ...
;                 for (int m = 0; m < 4; ++m) { const size_t off = (size_t)(row0 + ai * HALF + m * 16) * E + c;
;                     float y[8], x0[8];
; #pragma unroll
;                     for (int n = 0; n < 2; ++n)
; #pragma unroll
;                         for (int j = 0; j < 4; ++j) { const float cur = acc[ai][bj][m][n][j], prev = (m > 0) ? acc[ai][bj][m > 0 ? m - 1 : 0][n][j] : 0.f;
;                             const float x1 = row_ror<1>(s1 ? prev : cur), x2 = row_ror<2>(s2 ? prev : cur), x3 = row_ror<3>(s3 ? prev : cur);
;                             x0[4 * n + j] = cur;
;                             y[4 * n + j] = bb[n][j] + w0[n][j] * x3 + w1[n][j] * x2 + w2[n][j] * x1 + w3[n][j] * cur; }
;                     if (m > 0 || fr >= 3) { u32x4 w; w.x = cvt_pk_bf16(y[0], y[1]); w.y = cvt_pk_bf16(y[2], y[3]); w.z = cvt_pk_bf16(y[4], y[5]); w.w = cvt_pk_bf16(y[6], y[7]);
;                         *(u32x4*)(XC + off) = w; }
;                     if ((m == 0 && fr < 3) || (m == 3 && fr >= 13)) { u32x4 w; w.x = cvt_pk_bf16(x0[0], x0[1]); w.y = cvt_pk_bf16(x0[2], x0[3]); w.z = cvt_pk_bf16(x0[4], x0[5]); w.w = cvt_pk_bf16(x0[6], x0[7]);
;                         *(u32x4*)(XBE + off) = w; } }
	v_cndmask_b32_e64 v131, v33, 0, s[8:9]
	v_fmac_f32_dpp v134, v128, v184 row_ror:3 row_mask:0xf bank_mask:0xf
	v_fma_f32 v135, v209, v33, v217
	v_cndmask_b32_e64 v126, v26, 0, s[4:5]
	v_fmac_f32_dpp v135, v129, v201 row_ror:1 row_mask:0xf bank_mask:0xf
	v_cndmask_b32_e64 v127, v26, 0, s[6:7]
	v_fmac_f32_dpp v135, v130, v193 row_ror:2 row_mask:0xf bank_mask:0xf
	v_cndmask_b32_e64 v128, v26, 0, s[8:9]
	v_fmac_f32_dpp v135, v131, v185 row_ror:3 row_mask:0xf bank_mask:0xf
	v_fma_f32 v136, v210, v26, v218
	v_cndmask_b32_e64 v129, v27, 0, s[4:5]
	v_fmac_f32_dpp v136, v126, v202 row_ror:1 row_mask:0xf bank_mask:0xf
	v_cndmask_b32_e64 v130, v27, 0, s[6:7]
	v_fmac_f32_dpp v136, v127, v194 row_ror:2 row_mask:0xf bank_mask:0xf
	v_cndmask_b32_e64 v131, v27, 0, s[8:9]
	v_fmac_f32_dpp v136, v128, v186 row_ror:3 row_mask:0xf bank_mask:0xf
	v_fma_f32 v137, v211, v27, v219
	v_cndmask_b32_e64 v126, v28, 0, s[4:5]
	v_fmac_f32_dpp v137, v129, v203 row_ror:1 row_mask:0xf bank_mask:0xf
	v_cndmask_b32_e64 v127, v28, 0, s[6:7]
	v_fmac_f32_dpp v137, v130, v195 row_ror:2 row_mask:0xf bank_mask:0xf
	v_cndmask_b32_e64 v128, v28, 0, s[8:9]
	v_fmac_f32_dpp v137, v131, v187 row_ror:3 row_mask:0xf bank_mask:0xf
	v_fma_f32 v138, v212, v28, v220
	v_cndmask_b32_e64 v129, v29, 0, s[4:5]
	v_fmac_f32_dpp v138, v126, v204 row_ror:1 row_mask:0xf bank_mask:0xf
	v_cndmask_b32_e64 v130, v29, 0, s[6:7]
	v_fmac_f32_dpp v138, v127, v196 row_ror:2 row_mask:0xf bank_mask:0xf
	v_cndmask_b32_e64 v131, v29, 0, s[8:9]
	v_fmac_f32_dpp v138, v128, v188 row_ror:3 row_mask:0xf bank_mask:0xf
	v_fma_f32 v139, v213, v29, v221
	v_fmac_f32_dpp v139, v129, v205 row_ror:1 row_mask:0xf bank_mask:0xf
	v_fmac_f32_dpp v139, v130, v197 row_ror:2 row_mask:0xf bank_mask:0xf
	v_fmac_f32_dpp v139, v131, v189 row_ror:3 row_mask:0xf bank_mask:0xf
	v_cvt_pk_bf16_f32 v162, v132, v133
	v_cvt_pk_bf16_f32 v163, v134, v135
	v_cvt_pk_bf16_f32 v164, v136, v137
	v_cvt_pk_bf16_f32 v165, v138, v139
	v_cvt_pk_bf16_f32 v110, v30, v31
	v_cvt_pk_bf16_f32 v111, v32, v33
	v_cvt_pk_bf16_f32 v112, v26, v27
	v_cvt_pk_bf16_f32 v113, v28, v29
	s_mov_b64 exec, s[10:11]
	global_store_dwordx4 v101, v[162:165], s[20:21] offset:256
	s_not_b64 exec, exec
	global_store_dwordx4 v101, v[110:113], s[22:23] offset:256
	s_mov_b64 exec, -1
	s_nop 1
	v_cndmask_b32_e64 v126, v22, v30, s[4:5]
	v_cndmask_b32_e64 v127, v22, v30, s[6:7]
	v_cndmask_b32_e64 v128, v22, v30, s[8:9]
	v_fma_f32 v132, v206, v22, v214
	v_cndmask_b32_e64 v129, v23, v31, s[4:5]
	v_fmac_f32_dpp v132, v126, v198 row_ror:1 row_mask:0xf bank_mask:0xf
	v_cndmask_b32_e64 v130, v23, v31, s[6:7]
	v_fmac_f32_dpp v132, v127, v190 row_ror:2 row_mask:0xf bank_mask:0xf
	v_cndmask_b32_e64 v131, v23, v31, s[8:9]
	v_fmac_f32_dpp v132, v128, v182 row_ror:3 row_mask:0xf bank_mask:0xf
	v_fma_f32 v133, v207, v23, v215
	v_cndmask_b32_e64 v126, v24, v32, s[4:5]
	v_fmac_f32_dpp v133, v129, v199 row_ror:1 row_mask:0xf bank_mask:0xf
	v_cndmask_b32_e64 v127, v24, v32, s[6:7]
	v_fmac_f32_dpp v133, v130, v191 row_ror:2 row_mask:0xf bank_mask:0xf
	v_cndmask_b32_e64 v128, v24, v32, s[8:9]
	v_fmac_f32_dpp v133, v131, v183 row_ror:3 row_mask:0xf bank_mask:0xf
	v_fma_f32 v134, v208, v24, v216
	v_cndmask_b32_e64 v129, v25, v33, s[4:5]
	v_fmac_f32_dpp v134, v126, v200 row_ror:1 row_mask:0xf bank_mask:0xf
	v_cndmask_b32_e64 v130, v25, v33, s[6:7]
	v_fmac_f32_dpp v134, v127, v192 row_ror:2 row_mask:0xf bank_mask:0xf
	v_cndmask_b32_e64 v131, v25, v33, s[8:9]
	v_fmac_f32_dpp v134, v128, v184 row_ror:3 row_mask:0xf bank_mask:0xf
	v_fma_f32 v135, v209, v25, v217
	v_cndmask_b32_e64 v126, v18, v26, s[4:5]
	v_fmac_f32_dpp v135, v129, v201 row_ror:1 row_mask:0xf bank_mask:0xf
	v_cndmask_b32_e64 v127, v18, v26, s[6:7]
	v_fmac_f32_dpp v135, v130, v193 row_ror:2 row_mask:0xf bank_mask:0xf
	v_cndmask_b32_e64 v128, v18, v26, s[8:9]
	v_fmac_f32_dpp v135, v131, v185 row_ror:3 row_mask:0xf bank_mask:0xf
	v_fma_f32 v136, v210, v18, v218
	v_cndmask_b32_e64 v129, v19, v27, s[4:5]
	v_fmac_f32_dpp v136, v126, v202 row_ror:1 row_mask:0xf bank_mask:0xf
	v_cndmask_b32_e64 v130, v19, v27, s[6:7]
	v_fmac_f32_dpp v136, v127, v194 row_ror:2 row_mask:0xf bank_mask:0xf
	v_cndmask_b32_e64 v131, v19, v27, s[8:9]
	v_fmac_f32_dpp v136, v128, v186 row_ror:3 row_mask:0xf bank_mask:0xf
	v_fma_f32 v137, v211, v19, v219
	v_cndmask_b32_e64 v126, v20, v28, s[4:5]
	v_fmac_f32_dpp v137, v129, v203 row_ror:1 row_mask:0xf bank_mask:0xf
	v_cndmask_b32_e64 v127, v20, v28, s[6:7]
	v_fmac_f32_dpp v137, v130, v195 row_ror:2 row_mask:0xf bank_mask:0xf
	v_cndmask_b32_e64 v128, v20, v28, s[8:9]
	v_fmac_f32_dpp v137, v131, v187 row_ror:3 row_mask:0xf bank_mask:0xf
	v_fma_f32 v138, v212, v20, v220
	v_cndmask_b32_e64 v129, v21, v29, s[4:5]
	v_fmac_f32_dpp v138, v126, v204 row_ror:1 row_mask:0xf bank_mask:0xf
	v_cndmask_b32_e64 v130, v21, v29, s[6:7]
	v_fmac_f32_dpp v138, v127, v196 row_ror:2 row_mask:0xf bank_mask:0xf
	v_cndmask_b32_e64 v131, v21, v29, s[8:9]
	v_fmac_f32_dpp v138, v128, v188 row_ror:3 row_mask:0xf bank_mask:0xf
	v_fma_f32 v139, v213, v21, v221
	v_fmac_f32_dpp v139, v129, v205 row_ror:1 row_mask:0xf bank_mask:0xf
	v_fmac_f32_dpp v139, v130, v197 row_ror:2 row_mask:0xf bank_mask:0xf
	v_fmac_f32_dpp v139, v131, v189 row_ror:3 row_mask:0xf bank_mask:0xf
	v_cvt_pk_bf16_f32 v166, v132, v133
	v_cvt_pk_bf16_f32 v167, v134, v135
	v_cvt_pk_bf16_f32 v168, v136, v137
	v_cvt_pk_bf16_f32 v169, v138, v139
	global_store_dwordx4 v102, v[166:169], s[20:21] offset:256
	s_nop 1
	v_cndmask_b32_e64 v126, v14, v22, s[4:5]
	v_cndmask_b32_e64 v127, v14, v22, s[6:7]
	v_cndmask_b32_e64 v128, v14, v22, s[8:9]
	v_fma_f32 v132, v206, v14, v214
	v_cndmask_b32_e64 v129, v15, v23, s[4:5]
; __device__ __forceinline__ unsigned cvt_pk_bf16(float lo, float hi) { unsigned r; asm volatile("v_cvt_pk_bf16_f32 %0, %1, %2" : "=v"(r) : "v"(lo), "v"(hi)); return r; }
; template <int K> __device__ __forceinline__ float row_ror(float v) { return __int_as_float(__builtin_amdgcn_update_dpp(0, __float_as_int(v), 0x120 + K, 0xF, 0xF, false)); }
;     EPI_ZERO_INIT
;     __device__ __forceinline__ void operator()(AccRef acc, const Unit& u, int sw) const {
;     ...
;                 for (int m = 0; m < 4; ++m) { const size_t off = (size_t)(row0 + ai * HALF + m * 16) * E + c;
;                     float y[8], x0[8];
; #pragma unroll
;                     for (int n = 0; n < 2; ++n)
; #pragma unroll
;                         for (int j = 0; j < 4; ++j) { const float cur = acc[ai][bj][m][n][j], prev = (m > 0) ? acc[ai][bj][m > 0 ? m - 1 : 0][n][j] : 0.f;
;                             const float x1 = row_ror<1>(s1 ? prev : cur), x2 = row_ror<2>(s2 ? prev : cur), x3 = row_ror<3>(s3 ? prev : cur);
;                             x0[4 * n + j] = cur;
;                             y[4 * n + j] = bb[n][j] + w0[n][j] * x3 + w1[n][j] * x2 + w2[n][j] * x1 + w3[n][j] * cur; }
;                     if (m > 0 || fr >= 3) { u32x4 w; w.x = cvt_pk_bf16(y[0], y[1]); w.y = cvt_pk_bf16(y[2], y[3]); w.z = cvt_pk_bf16(y[4], y[5]); w.w = cvt_pk_bf16(y[6], y[7]);
;                         *(u32x4*)(XC + off) = w; }
;                     if ((m == 0 && fr < 3) || (m == 3 && fr >= 13)) { u32x4 w; w.x = cvt_pk_bf16(x0[0], x0[1]); w.y = cvt_pk_bf16(x0[2], x0[3]); w.z = cvt_pk_bf16(x0[4], x0[5]); w.w = cvt_pk_bf16(x0[6], x0[7]);
;                         *(u32x4*)(XBE + off) = w; } }
	v_fmac_f32_dpp v132, v126, v198 row_ror:1 row_mask:0xf bank_mask:0xf
	v_cndmask_b32_e64 v130, v15, v23, s[6:7]
	v_fmac_f32_dpp v132, v127, v190 row_ror:2 row_mask:0xf bank_mask:0xf
	v_cndmask_b32_e64 v131, v15, v23, s[8:9]
	v_fmac_f32_dpp v132, v128, v182 row_ror:3 row_mask:0xf bank_mask:0xf
	v_fma_f32 v133, v207, v15, v215
	v_cndmask_b32_e64 v126, v16, v24, s[4:5]
	v_fmac_f32_dpp v133, v129, v199 row_ror:1 row_mask:0xf bank_mask:0xf
	v_cndmask_b32_e64 v127, v16, v24, s[6:7]
	v_fmac_f32_dpp v133, v130, v191 row_ror:2 row_mask:0xf bank_mask:0xf
	v_cndmask_b32_e64 v128, v16, v24, s[8:9]
	v_fmac_f32_dpp v133, v131, v183 row_ror:3 row_mask:0xf bank_mask:0xf
	v_fma_f32 v134, v208, v16, v216
	v_cndmask_b32_e64 v129, v17, v25, s[4:5]
	v_fmac_f32_dpp v134, v126, v200 row_ror:1 row_mask:0xf bank_mask:0xf
	v_cndmask_b32_e64 v130, v17, v25, s[6:7]
	v_fmac_f32_dpp v134, v127, v192 row_ror:2 row_mask:0xf bank_mask:0xf
	v_cndmask_b32_e64 v131, v17, v25, s[8:9]
	v_fmac_f32_dpp v134, v128, v184 row_ror:3 row_mask:0xf bank_mask:0xf
	v_fma_f32 v135, v209, v17, v217
	v_cndmask_b32_e64 v126, v10, v18, s[4:5]
	v_fmac_f32_dpp v135, v129, v201 row_ror:1 row_mask:0xf bank_mask:0xf
	v_cndmask_b32_e64 v127, v10, v18, s[6:7]
	v_fmac_f32_dpp v135, v130, v193 row_ror:2 row_mask:0xf bank_mask:0xf
	v_cndmask_b32_e64 v128, v10, v18, s[8:9]
	v_fmac_f32_dpp v135, v131, v185 row_ror:3 row_mask:0xf bank_mask:0xf
	v_fma_f32 v136, v210, v10, v218
	v_cndmask_b32_e64 v129, v11, v19, s[4:5]
	v_fmac_f32_dpp v136, v126, v202 row_ror:1 row_mask:0xf bank_mask:0xf
	v_cndmask_b32_e64 v130, v11, v19, s[6:7]
	v_fmac_f32_dpp v136, v127, v194 row_ror:2 row_mask:0xf bank_mask:0xf
	v_cndmask_b32_e64 v131, v11, v19, s[8:9]
	v_fmac_f32_dpp v136, v128, v186 row_ror:3 row_mask:0xf bank_mask:0xf
	v_fma_f32 v137, v211, v11, v219
	v_cndmask_b32_e64 v126, v12, v20, s[4:5]
	v_fmac_f32_dpp v137, v129, v203 row_ror:1 row_mask:0xf bank_mask:0xf
	v_cndmask_b32_e64 v127, v12, v20, s[6:7]
	v_fmac_f32_dpp v137, v130, v195 row_ror:2 row_mask:0xf bank_mask:0xf
	v_cndmask_b32_e64 v128, v12, v20, s[8:9]
	v_fmac_f32_dpp v137, v131, v187 row_ror:3 row_mask:0xf bank_mask:0xf
	v_fma_f32 v138, v212, v12, v220
	v_cndmask_b32_e64 v129, v13, v21, s[4:5]
	v_fmac_f32_dpp v138, v126, v204 row_ror:1 row_mask:0xf bank_mask:0xf
	v_cndmask_b32_e64 v130, v13, v21, s[6:7]
	v_fmac_f32_dpp v138, v127, v196 row_ror:2 row_mask:0xf bank_mask:0xf
	v_cndmask_b32_e64 v131, v13, v21, s[8:9]
	v_fmac_f32_dpp v138, v128, v188 row_ror:3 row_mask:0xf bank_mask:0xf
	v_fma_f32 v139, v213, v13, v221
	v_fmac_f32_dpp v139, v129, v205 row_ror:1 row_mask:0xf bank_mask:0xf
	v_fmac_f32_dpp v139, v130, v197 row_ror:2 row_mask:0xf bank_mask:0xf
	v_fmac_f32_dpp v139, v131, v189 row_ror:3 row_mask:0xf bank_mask:0xf
	v_cvt_pk_bf16_f32 v162, v132, v133
	v_cvt_pk_bf16_f32 v163, v134, v135
	v_cvt_pk_bf16_f32 v164, v136, v137
	v_cvt_pk_bf16_f32 v165, v138, v139
	global_store_dwordx4 v103, v[162:165], s[20:21] offset:256
	s_nop 1
	v_cndmask_b32_e64 v126, v6, v14, s[4:5]
	v_cndmask_b32_e64 v127, v6, v14, s[6:7]
	v_cndmask_b32_e64 v128, v6, v14, s[8:9]
	v_fma_f32 v132, v206, v6, v214
	v_cndmask_b32_e64 v129, v7, v15, s[4:5]
	v_fmac_f32_dpp v132, v126, v198 row_ror:1 row_mask:0xf bank_mask:0xf
	v_cndmask_b32_e64 v130, v7, v15, s[6:7]
	v_fmac_f32_dpp v132, v127, v190 row_ror:2 row_mask:0xf bank_mask:0xf
	v_cndmask_b32_e64 v131, v7, v15, s[8:9]
	v_fmac_f32_dpp v132, v128, v182 row_ror:3 row_mask:0xf bank_mask:0xf
	v_fma_f32 v133, v207, v7, v215
	v_cndmask_b32_e64 v126, v8, v16, s[4:5]
	v_fmac_f32_dpp v133, v129, v199 row_ror:1 row_mask:0xf bank_mask:0xf
	v_cndmask_b32_e64 v127, v8, v16, s[6:7]
	v_fmac_f32_dpp v133, v130, v191 row_ror:2 row_mask:0xf bank_mask:0xf
	v_cndmask_b32_e64 v128, v8, v16, s[8:9]
	v_fmac_f32_dpp v133, v131, v183 row_ror:3 row_mask:0xf bank_mask:0xf
	v_fma_f32 v134, v208, v8, v216
	v_cndmask_b32_e64 v129, v9, v17, s[4:5]
	v_fmac_f32_dpp v134, v126, v200 row_ror:1 row_mask:0xf bank_mask:0xf
	v_cndmask_b32_e64 v130, v9, v17, s[6:7]
	v_fmac_f32_dpp v134, v127, v192 row_ror:2 row_mask:0xf bank_mask:0xf
	v_cndmask_b32_e64 v131, v9, v17, s[8:9]
	v_fmac_f32_dpp v134, v128, v184 row_ror:3 row_mask:0xf bank_mask:0xf
	v_fma_f32 v135, v209, v9, v217
	v_cndmask_b32_e64 v126, v2, v10, s[4:5]
	v_fmac_f32_dpp v135, v129, v201 row_ror:1 row_mask:0xf bank_mask:0xf
	v_cndmask_b32_e64 v127, v2, v10, s[6:7]
	v_fmac_f32_dpp v135, v130, v193 row_ror:2 row_mask:0xf bank_mask:0xf
	v_cndmask_b32_e64 v128, v2, v10, s[8:9]
	v_fmac_f32_dpp v135, v131, v185 row_ror:3 row_mask:0xf bank_mask:0xf
	v_fma_f32 v136, v210, v2, v218
	v_cndmask_b32_e64 v129, v3, v11, s[4:5]
	v_fmac_f32_dpp v136, v126, v202 row_ror:1 row_mask:0xf bank_mask:0xf
	v_cndmask_b32_e64 v130, v3, v11, s[6:7]
	v_fmac_f32_dpp v136, v127, v194 row_ror:2 row_mask:0xf bank_mask:0xf
	v_cndmask_b32_e64 v131, v3, v11, s[8:9]
	v_fmac_f32_dpp v136, v128, v186 row_ror:3 row_mask:0xf bank_mask:0xf
	v_fma_f32 v137, v211, v3, v219
	v_cndmask_b32_e64 v126, v4, v12, s[4:5]
	v_fmac_f32_dpp v137, v129, v203 row_ror:1 row_mask:0xf bank_mask:0xf
	v_cndmask_b32_e64 v127, v4, v12, s[6:7]
	v_fmac_f32_dpp v137, v130, v195 row_ror:2 row_mask:0xf bank_mask:0xf
	v_cndmask_b32_e64 v128, v4, v12, s[8:9]
	v_fmac_f32_dpp v137, v131, v187 row_ror:3 row_mask:0xf bank_mask:0xf
	v_fma_f32 v138, v212, v4, v220
	v_cndmask_b32_e64 v129, v5, v13, s[4:5]
	v_fmac_f32_dpp v138, v126, v204 row_ror:1 row_mask:0xf bank_mask:0xf
	v_cndmask_b32_e64 v130, v5, v13, s[6:7]
	v_fmac_f32_dpp v138, v127, v196 row_ror:2 row_mask:0xf bank_mask:0xf
	v_cndmask_b32_e64 v131, v5, v13, s[8:9]
	v_fmac_f32_dpp v138, v128, v188 row_ror:3 row_mask:0xf bank_mask:0xf
	v_fma_f32 v139, v213, v5, v221
	v_fmac_f32_dpp v139, v129, v205 row_ror:1 row_mask:0xf bank_mask:0xf
	v_fmac_f32_dpp v139, v130, v197 row_ror:2 row_mask:0xf bank_mask:0xf
	v_fmac_f32_dpp v139, v131, v189 row_ror:3 row_mask:0xf bank_mask:0xf
	v_cvt_pk_bf16_f32 v166, v132, v133
	v_cvt_pk_bf16_f32 v167, v134, v135
	v_cvt_pk_bf16_f32 v168, v136, v137
	v_cvt_pk_bf16_f32 v169, v138, v139
	v_cvt_pk_bf16_f32 v118, v6, v7
	v_cvt_pk_bf16_f32 v119, v8, v9
	v_cvt_pk_bf16_f32 v120, v2, v3
	v_cvt_pk_bf16_f32 v121, v4, v5
	global_store_dwordx4 v104, v[166:169], s[20:21] offset:256
	s_mov_b64 exec, s[8:9]
	global_store_dwordx4 v104, v[118:121], s[22:23] offset:256
	s_mov_b64 exec, -1
	s_nop 1
	s_branch .LBB0_259
